# GEMM K-loop back edges: counter/pointer SALU block moved in front of the closing barrier (6 GEMM instances)
# speedup vs baseline: 1.0078x; 1.0078x over previous
; #define PG8_STAGE(bufoff, gbase, voff) do { _Pragma("unroll") for (int _i = 0; _i < 2; ++_i) \
;         __builtin_amdgcn_global_load_lds((const unsigned*)((const char*)(gbase) + (voff)[_i]), (PG8_LAS unsigned*)(lds + (bufoff) + ldsw + _i * 8192), 16, 0, 0); } while (0)
; #define PG8_LDA(dst, b, h) do { _Pragma("unroll") for (int m = 0; m < 4; ++m) _Pragma("unroll") for (int k = 0; k < 2; ++k) dst[m][k] = *(const PG8_LAS bf16x8*)(lds + PG8_SA(b, h) + aoff + m * 2048 + k * 1024); } while (0)
; #define PG8_LDB(dst, b, h) do { _Pragma("unroll") for (int n = 0; n < 2; ++n) _Pragma("unroll") for (int k = 0; k < 2; ++k) dst[n][k] = *(const PG8_LAS bf16x8*)(lds + PG8_SB(b, h) + boff + n * 2048 + k * 1024); } while (0)
; #define PG8_MMA(ai, bj, At, Bt) do { __builtin_amdgcn_s_setprio(1); _Pragma("unroll") for (int m = 0; m < 4; ++m) _Pragma("unroll") for (int n = 0; n < 2; ++n) _Pragma("unroll") for (int k = 0; k < 2; ++k) \
;         acc[ai][bj][m][n] = __builtin_amdgcn_mfma_f32_16x16x32_bf16(Bt[n][k], At[m][k], acc[ai][bj][m][n], 0, 0, 0); __builtin_amdgcn_s_setprio(0); } while (0)
; #define PG8_WAIT_V(n) asm volatile("s_waitcnt vmcnt(" #n ")" ::: "memory")
; #define PG8_WAIT_L(n) asm volatile("s_waitcnt lgkmcnt(" #n ")" ::: "memory")
; #define PG8_BAR __builtin_amdgcn_s_barrier()
; #define PG8_SCHED __builtin_amdgcn_sched_barrier(0)
; template <class Epi, class Sched, bool ALIGN_EPI = false, bool SP2 = false>
; __device__ __forceinline__ void gemm_phase(PG8_LAS unsigned char* lds, const Gemm g, const Sched& S, const Epi& E) {
;     ...
;             PG8_LDB(B0, 0, 0); PG8_LDB(B1, 0, 1); PG8_SCHED; PG8_LDA(At, 0, 0); PG8_STAGE(PG8_SA(1, 1), a1 + hstep, voffA);
;             PG8_WAIT_V(8); PG8_WAIT_L(0); PG8_BAR; PG8_MMA(0, 0, At, B0); PG8_MMA(0, 1, At, B1); PG8_BAR; PG8_SCHED;
;             PG8_LDA(At, 0, 1); PG8_STAGE(PG8_SB(0, 0), b2, voffB); PG8_STAGE(PG8_SB(0, 1), b2 + hstep, voffB); PG8_STAGE(PG8_SA(0, 0), a2, voffA);
;             PG8_WAIT_V(8); PG8_WAIT_L(0); PG8_BAR; PG8_MMA(1, 0, At, B0); PG8_MMA(1, 1, At, B1); PG8_BAR; PG8_SCHED;
.LBB0_192:
	ds_read_b128 v[128:131], v196
	ds_read_b128 v[132:135], v196 offset:1024
	ds_read_b128 v[162:165], v196 offset:2048
	ds_read_b128 v[166:169], v196 offset:3072
	ds_read_b128 v[172:175], v197
	s_waitcnt lgkmcnt(0)
	ds_read_b128 v[178:181], v197 offset:1024
	ds_read_b128 v[182:185], v197 offset:2048
	ds_read_b128 v[208:211], v197 offset:3072
	s_add_u32 s6, s4, 0xfffc0080
	s_addc_u32 s7, s5, -1
	s_cmp_eq_u32 s70, 12
	s_cselect_b32 s9, s36, s7
	s_cselect_b32 s8, s37, s6
	s_cselect_b32 s7, s49, s69
	s_cselect_b32 s6, s51, s68
	v_lshl_add_u64 v[244:245], s[4:5], 0, v[154:155]
	s_add_i32 m0, s61, 0xc000
	ds_read_b128 v[212:215], v198
	ds_read_b128 v[216:219], v198 offset:1024
	ds_read_b128 v[220:223], v198 offset:2048
	ds_read_b128 v[224:227], v198 offset:3072
	ds_read_b128 v[228:231], v198 offset:4096
	ds_read_b128 v[232:235], v198 offset:5120
	ds_read_b128 v[236:239], v198 offset:6144
	ds_read_b128 v[240:243], v198 offset:7168
	global_load_lds_dwordx4 v[244:245], off
	v_lshl_add_u64 v[244:245], s[4:5], 0, v[156:157]
	s_add_i32 m0, s61, 0xe000
	s_nop 0
	global_load_lds_dwordx4 v[244:245], off
	s_waitcnt vmcnt(8)
	s_waitcnt lgkmcnt(0)
	s_barrier
	s_setprio 1
	s_waitcnt lgkmcnt(0)
	v_mfma_f32_16x16x32_bf16 v[124:127], v[128:131], v[212:215], v[124:127]
	v_mfma_f32_16x16x32_bf16 v[120:123], v[162:165], v[212:215], v[120:123]
	v_mfma_f32_16x16x32_bf16 v[108:111], v[128:131], v[220:223], v[108:111]
	v_mfma_f32_16x16x32_bf16 v[104:107], v[162:165], v[220:223], v[104:107]
	v_mfma_f32_16x16x32_bf16 v[92:95], v[128:131], v[228:231], v[92:95]
	v_mfma_f32_16x16x32_bf16 v[88:91], v[162:165], v[228:231], v[88:91]
	v_mfma_f32_16x16x32_bf16 v[76:79], v[128:131], v[236:239], v[76:79]
	v_mfma_f32_16x16x32_bf16 v[72:75], v[162:165], v[236:239], v[72:75]
	v_mfma_f32_16x16x32_bf16 v[124:127], v[132:135], v[216:219], v[124:127]
	v_mfma_f32_16x16x32_bf16 v[120:123], v[166:169], v[216:219], v[120:123]
	v_mfma_f32_16x16x32_bf16 v[108:111], v[132:135], v[224:227], v[108:111]
	v_mfma_f32_16x16x32_bf16 v[104:107], v[166:169], v[224:227], v[104:107]
	v_mfma_f32_16x16x32_bf16 v[92:95], v[132:135], v[232:235], v[92:95]
	v_mfma_f32_16x16x32_bf16 v[88:91], v[166:169], v[232:235], v[88:91]
	v_mfma_f32_16x16x32_bf16 v[76:79], v[132:135], v[240:243], v[76:79]
	v_mfma_f32_16x16x32_bf16 v[72:75], v[166:169], v[240:243], v[72:75]
	s_setprio 0
	s_setprio 1
	v_mfma_f32_16x16x32_bf16 v[116:119], v[172:175], v[212:215], v[116:119]
	v_mfma_f32_16x16x32_bf16 v[112:115], v[182:185], v[212:215], v[112:115]
	v_mfma_f32_16x16x32_bf16 v[100:103], v[172:175], v[220:223], v[100:103]
	v_mfma_f32_16x16x32_bf16 v[96:99], v[182:185], v[220:223], v[96:99]
	v_mfma_f32_16x16x32_bf16 v[84:87], v[172:175], v[228:231], v[84:87]
	v_mfma_f32_16x16x32_bf16 v[80:83], v[182:185], v[228:231], v[80:83]
	v_mfma_f32_16x16x32_bf16 v[68:71], v[172:175], v[236:239], v[68:71]
	v_mfma_f32_16x16x32_bf16 v[64:67], v[182:185], v[236:239], v[64:67]
	v_mfma_f32_16x16x32_bf16 v[116:119], v[178:181], v[216:219], v[116:119]
	v_mfma_f32_16x16x32_bf16 v[112:115], v[208:211], v[216:219], v[112:115]
	v_mfma_f32_16x16x32_bf16 v[100:103], v[178:181], v[224:227], v[100:103]
	v_mfma_f32_16x16x32_bf16 v[96:99], v[208:211], v[224:227], v[96:99]
	v_mfma_f32_16x16x32_bf16 v[84:87], v[178:181], v[232:235], v[84:87]
	v_mfma_f32_16x16x32_bf16 v[80:83], v[208:211], v[232:235], v[80:83]
	v_mfma_f32_16x16x32_bf16 v[68:71], v[178:181], v[240:243], v[68:71]
	v_mfma_f32_16x16x32_bf16 v[64:67], v[208:211], v[240:243], v[64:67]
	s_setprio 0
	s_barrier
	s_add_i32 s80, s85, s72
	v_lshl_add_u64 v[244:245], s[6:7], 0, v[138:139]
	s_mov_b32 m0, s80
	ds_read_b128 v[212:215], v198 offset:16384
	ds_read_b128 v[216:219], v198 offset:17408
	ds_read_b128 v[220:223], v198 offset:18432
	ds_read_b128 v[224:227], v198 offset:19456
	ds_read_b128 v[228:231], v198 offset:20480
	ds_read_b128 v[232:235], v198 offset:21504
	ds_read_b128 v[236:239], v198 offset:22528
	ds_read_b128 v[240:243], v198 offset:23552
	global_load_lds_dwordx4 v[244:245], off
	s_add_i32 m0, s80, 0x2000
	s_add_u32 s80, s6, 0x40000
	v_lshl_add_u64 v[246:247], s[6:7], 0, v[142:143]
	s_addc_u32 s81, s7, 0
	s_add_i32 s82, s86, s72
	global_load_lds_dwordx4 v[246:247], off
	v_lshl_add_u64 v[248:249], s[80:81], 0, v[138:139]
	s_mov_b32 m0, s82
	v_lshl_add_u64 v[250:251], s[8:9], 0, v[140:141]
	global_load_lds_dwordx4 v[248:249], off
	v_lshl_add_u64 v[248:249], s[80:81], 0, v[142:143]
	s_add_i32 m0, s82, 0x2000
	s_nop 0
	global_load_lds_dwordx4 v[248:249], off
	v_lshl_add_u64 v[248:249], s[8:9], 0, v[136:137]
	s_mov_b32 m0, s61
	s_nop 0
	global_load_lds_dwordx4 v[248:249], off
	s_mov_b32 m0, s63
	s_nop 0
	global_load_lds_dwordx4 v[250:251], off
	s_waitcnt vmcnt(8)
	s_waitcnt lgkmcnt(0)
	s_barrier
; #define PG8_STAGE(bufoff, gbase, voff) do { _Pragma("unroll") for (int _i = 0; _i < 2; ++_i) \
;         __builtin_amdgcn_global_load_lds((const unsigned*)((const char*)(gbase) + (voff)[_i]), (PG8_LAS unsigned*)(lds + (bufoff) + ldsw + _i * 8192), 16, 0, 0); } while (0)
; #define PG8_LDA(dst, b, h) do { _Pragma("unroll") for (int m = 0; m < 4; ++m) _Pragma("unroll") for (int k = 0; k < 2; ++k) dst[m][k] = *(const PG8_LAS bf16x8*)(lds + PG8_SA(b, h) + aoff + m * 2048 + k * 1024); } while (0)
; #define PG8_LDB(dst, b, h) do { _Pragma("unroll") for (int n = 0; n < 2; ++n) _Pragma("unroll") for (int k = 0; k < 2; ++k) dst[n][k] = *(const PG8_LAS bf16x8*)(lds + PG8_SB(b, h) + boff + n * 2048 + k * 1024); } while (0)
; #define PG8_MMA(ai, bj, At, Bt) do { __builtin_amdgcn_s_setprio(1); _Pragma("unroll") for (int m = 0; m < 4; ++m) _Pragma("unroll") for (int n = 0; n < 2; ++n) _Pragma("unroll") for (int k = 0; k < 2; ++k) \
;         acc[ai][bj][m][n] = __builtin_amdgcn_mfma_f32_16x16x32_bf16(Bt[n][k], At[m][k], acc[ai][bj][m][n], 0, 0, 0); __builtin_amdgcn_s_setprio(0); } while (0)
; #define PG8_WAIT_V(n) asm volatile("s_waitcnt vmcnt(" #n ")" ::: "memory")
; #define PG8_WAIT_L(n) asm volatile("s_waitcnt lgkmcnt(" #n ")" ::: "memory")
; #define PG8_BAR __builtin_amdgcn_s_barrier()
; #define PG8_SCHED __builtin_amdgcn_sched_barrier(0)
; template <class Epi, class Sched, bool ALIGN_EPI = false, bool SP2 = false>
; __device__ __forceinline__ void gemm_phase(PG8_LAS unsigned char* lds, const Gemm g, const Sched& S, const Epi& E) {
;     ...
;             PG8_WAIT_V(8); PG8_WAIT_L(0); PG8_BAR; PG8_MMA(1, 0, At, B0); PG8_MMA(1, 1, At, B1); PG8_BAR; PG8_SCHED;
;             PG8_LDB(B0, 1, 0); PG8_LDB(B1, 1, 1); PG8_SCHED; PG8_LDA(At, 1, 0); PG8_STAGE(PG8_SA(0, 1), a2 + hstep, voffA);
;             PG8_WAIT_V(8); PG8_WAIT_L(0); PG8_BAR; PG8_MMA(0, 0, At, B0); PG8_MMA(0, 1, At, B1); PG8_BAR; PG8_SCHED;
;             PG8_LDA(At, 1, 1); PG8_STAGE(PG8_SB(1, 0), b3, voffB); PG8_STAGE(PG8_SB(1, 1), b3 + hstep, voffB); PG8_STAGE(PG8_SA(1, 0), a3, voffA);
	s_setprio 1
	s_waitcnt lgkmcnt(0)
	v_mfma_f32_16x16x32_bf16 v[60:63], v[128:131], v[212:215], v[60:63]
	v_mfma_f32_16x16x32_bf16 v[56:59], v[162:165], v[212:215], v[56:59]
	v_mfma_f32_16x16x32_bf16 v[44:47], v[128:131], v[220:223], v[44:47]
	v_mfma_f32_16x16x32_bf16 v[40:43], v[162:165], v[220:223], v[40:43]
	v_mfma_f32_16x16x32_bf16 v[28:31], v[128:131], v[228:231], v[28:31]
	v_mfma_f32_16x16x32_bf16 v[24:27], v[162:165], v[228:231], v[24:27]
	v_mfma_f32_16x16x32_bf16 v[12:15], v[128:131], v[236:239], v[12:15]
	v_mfma_f32_16x16x32_bf16 v[8:11], v[162:165], v[236:239], v[8:11]
	v_mfma_f32_16x16x32_bf16 v[60:63], v[132:135], v[216:219], v[60:63]
	v_mfma_f32_16x16x32_bf16 v[56:59], v[166:169], v[216:219], v[56:59]
	v_mfma_f32_16x16x32_bf16 v[44:47], v[132:135], v[224:227], v[44:47]
	v_mfma_f32_16x16x32_bf16 v[40:43], v[166:169], v[224:227], v[40:43]
	v_mfma_f32_16x16x32_bf16 v[28:31], v[132:135], v[232:235], v[28:31]
	v_mfma_f32_16x16x32_bf16 v[24:27], v[166:169], v[232:235], v[24:27]
	v_mfma_f32_16x16x32_bf16 v[12:15], v[132:135], v[240:243], v[12:15]
	v_mfma_f32_16x16x32_bf16 v[8:11], v[166:169], v[240:243], v[8:11]
	s_setprio 0
	s_setprio 1
	v_mfma_f32_16x16x32_bf16 v[52:55], v[172:175], v[212:215], v[52:55]
	v_mfma_f32_16x16x32_bf16 v[48:51], v[182:185], v[212:215], v[48:51]
	v_mfma_f32_16x16x32_bf16 v[36:39], v[172:175], v[220:223], v[36:39]
	v_mfma_f32_16x16x32_bf16 v[32:35], v[182:185], v[220:223], v[32:35]
	v_mfma_f32_16x16x32_bf16 v[20:23], v[172:175], v[228:231], v[20:23]
	v_mfma_f32_16x16x32_bf16 v[16:19], v[182:185], v[228:231], v[16:19]
	v_mfma_f32_16x16x32_bf16 v[4:7], v[172:175], v[236:239], v[4:7]
	v_mfma_f32_16x16x32_bf16 v[0:3], v[182:185], v[236:239], v[0:3]
	v_mfma_f32_16x16x32_bf16 v[52:55], v[178:181], v[216:219], v[52:55]
	v_mfma_f32_16x16x32_bf16 v[48:51], v[208:211], v[216:219], v[48:51]
	v_mfma_f32_16x16x32_bf16 v[36:39], v[178:181], v[224:227], v[36:39]
	v_mfma_f32_16x16x32_bf16 v[32:35], v[208:211], v[224:227], v[32:35]
	v_mfma_f32_16x16x32_bf16 v[20:23], v[178:181], v[232:235], v[20:23]
	v_mfma_f32_16x16x32_bf16 v[16:19], v[208:211], v[232:235], v[16:19]
	v_mfma_f32_16x16x32_bf16 v[4:7], v[178:181], v[240:243], v[4:7]
	v_mfma_f32_16x16x32_bf16 v[0:3], v[208:211], v[240:243], v[0:3]
	s_setprio 0
	s_barrier
	s_add_i32 s80, 0, 0x18000
	v_add_u32_e32 v144, s80, v186
	s_add_i32 s81, 0, 0x1c000
	ds_read_b128 v[128:131], v144
	ds_read_b128 v[132:135], v144 offset:1024
	ds_read_b128 v[162:165], v144 offset:2048
	ds_read_b128 v[166:169], v144 offset:3072
	v_add_u32_e32 v144, s81, v186
	ds_read_b128 v[172:175], v144
	ds_read_b128 v[178:181], v144 offset:1024
	ds_read_b128 v[182:185], v144 offset:2048
	ds_read_b128 v[208:211], v144 offset:3072
	s_add_u32 s8, s8, 0x40000
	s_addc_u32 s9, s9, 0
	s_mov_b32 m0, s73
	v_lshl_add_u64 v[252:253], s[8:9], 0, v[136:137]
	ds_read_b128 v[212:215], v198 offset:32768
	ds_read_b128 v[216:219], v198 offset:33792
	ds_read_b128 v[220:223], v198 offset:34816
	ds_read_b128 v[224:227], v198 offset:35840
	ds_read_b128 v[228:231], v198 offset:36864
	ds_read_b128 v[232:235], v198 offset:37888
	ds_read_b128 v[236:239], v198 offset:38912
	ds_read_b128 v[240:243], v198 offset:39936
	global_load_lds_dwordx4 v[252:253], off
	v_lshl_add_u64 v[252:253], s[8:9], 0, v[140:141]
	s_mov_b32 m0, s74
	s_nop 0
	global_load_lds_dwordx4 v[252:253], off
	s_waitcnt vmcnt(8)
	s_waitcnt lgkmcnt(0)
	s_barrier
	s_setprio 1
	s_waitcnt lgkmcnt(0)
	v_mfma_f32_16x16x32_bf16 v[124:127], v[128:131], v[212:215], v[124:127]
	v_mfma_f32_16x16x32_bf16 v[120:123], v[162:165], v[212:215], v[120:123]
	v_mfma_f32_16x16x32_bf16 v[108:111], v[128:131], v[220:223], v[108:111]
	v_mfma_f32_16x16x32_bf16 v[104:107], v[162:165], v[220:223], v[104:107]
	v_mfma_f32_16x16x32_bf16 v[92:95], v[128:131], v[228:231], v[92:95]
	v_mfma_f32_16x16x32_bf16 v[88:91], v[162:165], v[228:231], v[88:91]
	v_mfma_f32_16x16x32_bf16 v[76:79], v[128:131], v[236:239], v[76:79]
	v_mfma_f32_16x16x32_bf16 v[72:75], v[162:165], v[236:239], v[72:75]
	v_mfma_f32_16x16x32_bf16 v[124:127], v[132:135], v[216:219], v[124:127]
	v_mfma_f32_16x16x32_bf16 v[120:123], v[166:169], v[216:219], v[120:123]
	v_mfma_f32_16x16x32_bf16 v[108:111], v[132:135], v[224:227], v[108:111]
	v_mfma_f32_16x16x32_bf16 v[104:107], v[166:169], v[224:227], v[104:107]
	v_mfma_f32_16x16x32_bf16 v[92:95], v[132:135], v[232:235], v[92:95]
	v_mfma_f32_16x16x32_bf16 v[88:91], v[166:169], v[232:235], v[88:91]
	v_mfma_f32_16x16x32_bf16 v[76:79], v[132:135], v[240:243], v[76:79]
	v_mfma_f32_16x16x32_bf16 v[72:75], v[166:169], v[240:243], v[72:75]
	s_setprio 0
	s_setprio 1
	v_mfma_f32_16x16x32_bf16 v[116:119], v[172:175], v[212:215], v[116:119]
	v_mfma_f32_16x16x32_bf16 v[112:115], v[182:185], v[212:215], v[112:115]
	v_mfma_f32_16x16x32_bf16 v[100:103], v[172:175], v[220:223], v[100:103]
	v_mfma_f32_16x16x32_bf16 v[96:99], v[182:185], v[220:223], v[96:99]
	v_mfma_f32_16x16x32_bf16 v[84:87], v[172:175], v[228:231], v[84:87]
	v_mfma_f32_16x16x32_bf16 v[80:83], v[182:185], v[228:231], v[80:83]
	v_mfma_f32_16x16x32_bf16 v[68:71], v[172:175], v[236:239], v[68:71]
	v_mfma_f32_16x16x32_bf16 v[64:67], v[182:185], v[236:239], v[64:67]
	v_mfma_f32_16x16x32_bf16 v[116:119], v[178:181], v[216:219], v[116:119]
	v_mfma_f32_16x16x32_bf16 v[112:115], v[208:211], v[216:219], v[112:115]
	v_mfma_f32_16x16x32_bf16 v[100:103], v[178:181], v[224:227], v[100:103]
	v_mfma_f32_16x16x32_bf16 v[96:99], v[208:211], v[224:227], v[96:99]
	v_mfma_f32_16x16x32_bf16 v[84:87], v[178:181], v[232:235], v[84:87]
	v_mfma_f32_16x16x32_bf16 v[80:83], v[208:211], v[232:235], v[80:83]
	v_mfma_f32_16x16x32_bf16 v[68:71], v[178:181], v[240:243], v[68:71]
	v_mfma_f32_16x16x32_bf16 v[64:67], v[208:211], v[240:243], v[64:67]
	s_setprio 0
	s_barrier
; #define PG8_STAGE(bufoff, gbase, voff) do { _Pragma("unroll") for (int _i = 0; _i < 2; ++_i) \
;         __builtin_amdgcn_global_load_lds((const unsigned*)((const char*)(gbase) + (voff)[_i]), (PG8_LAS unsigned*)(lds + (bufoff) + ldsw + _i * 8192), 16, 0, 0); } while (0)
; #define PG8_LDA(dst, b, h) do { _Pragma("unroll") for (int m = 0; m < 4; ++m) _Pragma("unroll") for (int k = 0; k < 2; ++k) dst[m][k] = *(const PG8_LAS bf16x8*)(lds + PG8_SA(b, h) + aoff + m * 2048 + k * 1024); } while (0)
; #define PG8_MMA(ai, bj, At, Bt) do { __builtin_amdgcn_s_setprio(1); _Pragma("unroll") for (int m = 0; m < 4; ++m) _Pragma("unroll") for (int n = 0; n < 2; ++n) _Pragma("unroll") for (int k = 0; k < 2; ++k) \
;         acc[ai][bj][m][n] = __builtin_amdgcn_mfma_f32_16x16x32_bf16(Bt[n][k], At[m][k], acc[ai][bj][m][n], 0, 0, 0); __builtin_amdgcn_s_setprio(0); } while (0)
; #define PG8_WAIT_V(n) asm volatile("s_waitcnt vmcnt(" #n ")" ::: "memory")
; #define PG8_WAIT_L(n) asm volatile("s_waitcnt lgkmcnt(" #n ")" ::: "memory")
; #define PG8_BAR __builtin_amdgcn_s_barrier()
; #define PG8_SCHED __builtin_amdgcn_sched_barrier(0)
; template <class Epi, class Sched, bool ALIGN_EPI = false, bool SP2 = false>
; __device__ __forceinline__ void gemm_phase(PG8_LAS unsigned char* lds, const Gemm g, const Sched& S, const Epi& E) {
;     ...
;         for (int t = 0; t < nt; t += 2) {
;     ...
;             PG8_LDA(At, 1, 1); PG8_STAGE(PG8_SB(1, 0), b3, voffB); PG8_STAGE(PG8_SB(1, 1), b3 + hstep, voffB); PG8_STAGE(PG8_SA(1, 0), a3, voffA);
;             PG8_WAIT_V(8); PG8_WAIT_L(0); PG8_BAR; PG8_MMA(1, 0, At, B0); PG8_MMA(1, 1, At, B1); PG8_BAR; PG8_SCHED;
	s_add_i32 s8, s80, s72
	v_lshl_add_u64 v[244:245], v[244:245], 0, s[26:27]
	s_mov_b32 m0, s8
	ds_read_b128 v[212:215], v198 offset:49152
	ds_read_b128 v[216:219], v198 offset:50176
	ds_read_b128 v[220:223], v198 offset:51200
	ds_read_b128 v[224:227], v198 offset:52224
	ds_read_b128 v[228:231], v198 offset:53248
	ds_read_b128 v[232:235], v198 offset:54272
	ds_read_b128 v[236:239], v198 offset:55296
	ds_read_b128 v[240:243], v198 offset:56320
	global_load_lds_dwordx4 v[244:245], off
	s_add_i32 m0, s8, 0x2000
	s_add_u32 s6, s6, 0x40080
	v_lshl_add_u64 v[244:245], v[246:247], 0, s[26:27]
	s_addc_u32 s7, s7, 0
	s_add_i32 s8, s81, s72
	global_load_lds_dwordx4 v[244:245], off
	v_lshl_add_u64 v[244:245], s[6:7], 0, v[138:139]
	s_mov_b32 m0, s8
	s_nop 0
	global_load_lds_dwordx4 v[244:245], off
	v_lshl_add_u64 v[244:245], s[6:7], 0, v[142:143]
	s_add_i32 m0, s8, 0x2000
	s_nop 0
	global_load_lds_dwordx4 v[244:245], off
	v_lshl_add_u64 v[244:245], v[248:249], 0, s[26:27]
	s_mov_b32 m0, s77
	s_nop 0
	global_load_lds_dwordx4 v[244:245], off
	v_lshl_add_u64 v[244:245], v[250:251], 0, s[26:27]
	s_mov_b32 m0, s78
	s_nop 0
	global_load_lds_dwordx4 v[244:245], off
	s_waitcnt vmcnt(8)
	s_waitcnt lgkmcnt(0)
	s_barrier
	s_setprio 1
	s_waitcnt lgkmcnt(0)
	v_mfma_f32_16x16x32_bf16 v[60:63], v[128:131], v[212:215], v[60:63]
	v_mfma_f32_16x16x32_bf16 v[56:59], v[162:165], v[212:215], v[56:59]
	v_mfma_f32_16x16x32_bf16 v[44:47], v[128:131], v[220:223], v[44:47]
	v_mfma_f32_16x16x32_bf16 v[40:43], v[162:165], v[220:223], v[40:43]
	v_mfma_f32_16x16x32_bf16 v[28:31], v[128:131], v[228:231], v[28:31]
	v_mfma_f32_16x16x32_bf16 v[24:27], v[162:165], v[228:231], v[24:27]
	v_mfma_f32_16x16x32_bf16 v[12:15], v[128:131], v[236:239], v[12:15]
	v_mfma_f32_16x16x32_bf16 v[8:11], v[162:165], v[236:239], v[8:11]
	v_mfma_f32_16x16x32_bf16 v[60:63], v[132:135], v[216:219], v[60:63]
	v_mfma_f32_16x16x32_bf16 v[56:59], v[166:169], v[216:219], v[56:59]
	v_mfma_f32_16x16x32_bf16 v[44:47], v[132:135], v[224:227], v[44:47]
	v_mfma_f32_16x16x32_bf16 v[40:43], v[166:169], v[224:227], v[40:43]
	v_mfma_f32_16x16x32_bf16 v[28:31], v[132:135], v[232:235], v[28:31]
	v_mfma_f32_16x16x32_bf16 v[24:27], v[166:169], v[232:235], v[24:27]
	v_mfma_f32_16x16x32_bf16 v[12:15], v[132:135], v[240:243], v[12:15]
	v_mfma_f32_16x16x32_bf16 v[8:11], v[166:169], v[240:243], v[8:11]
	s_setprio 0
	s_setprio 1
	v_mfma_f32_16x16x32_bf16 v[52:55], v[172:175], v[212:215], v[52:55]
	v_mfma_f32_16x16x32_bf16 v[48:51], v[182:185], v[212:215], v[48:51]
	v_mfma_f32_16x16x32_bf16 v[36:39], v[172:175], v[220:223], v[36:39]
	v_mfma_f32_16x16x32_bf16 v[32:35], v[182:185], v[220:223], v[32:35]
	v_mfma_f32_16x16x32_bf16 v[20:23], v[172:175], v[228:231], v[20:23]
	v_mfma_f32_16x16x32_bf16 v[16:19], v[182:185], v[228:231], v[16:19]
	v_mfma_f32_16x16x32_bf16 v[4:7], v[172:175], v[236:239], v[4:7]
	v_mfma_f32_16x16x32_bf16 v[0:3], v[182:185], v[236:239], v[0:3]
	v_mfma_f32_16x16x32_bf16 v[52:55], v[178:181], v[216:219], v[52:55]
	v_mfma_f32_16x16x32_bf16 v[48:51], v[208:211], v[216:219], v[48:51]
	v_mfma_f32_16x16x32_bf16 v[36:39], v[178:181], v[224:227], v[36:39]
	v_mfma_f32_16x16x32_bf16 v[32:35], v[208:211], v[224:227], v[32:35]
	v_mfma_f32_16x16x32_bf16 v[20:23], v[178:181], v[232:235], v[20:23]
	v_mfma_f32_16x16x32_bf16 v[16:19], v[208:211], v[232:235], v[16:19]
	v_mfma_f32_16x16x32_bf16 v[4:7], v[178:181], v[240:243], v[4:7]
	v_mfma_f32_16x16x32_bf16 v[0:3], v[208:211], v[240:243], v[0:3]
	s_setprio 0
	s_add_i32 s70, s70, 2
	s_add_u32 s4, s4, 0x100
	s_addc_u32 s5, s5, 0
	s_add_u32 s68, s68, 0x100
	s_addc_u32 s69, s69, 0
	s_cmp_gt_u32 s70, 13
	s_barrier
	s_cbranch_scc0 .LBB0_192
	s_and_b64 vcc, exec, s[28:29]
	s_cbranch_vccnz .LBB0_197
	s_cmp_gt_i32 s62, 5
	s_mov_b64 s[4:5], -1
	s_cbranch_scc1 .LBB0_198

; #define PG8_STAGE(bufoff, gbase, voff) do { _Pragma("unroll") for (int _i = 0; _i < 2; ++_i) \
;         __builtin_amdgcn_global_load_lds((const unsigned*)((const char*)(gbase) + (voff)[_i]), (PG8_LAS unsigned*)(lds + (bufoff) + ldsw + _i * 8192), 16, 0, 0); } while (0)
; #define PG8_LDA(dst, b, h) do { _Pragma("unroll") for (int m = 0; m < 4; ++m) _Pragma("unroll") for (int k = 0; k < 2; ++k) dst[m][k] = *(const PG8_LAS bf16x8*)(lds + PG8_SA(b, h) + aoff + m * 2048 + k * 1024); } while (0)
; #define PG8_LDB(dst, b, h) do { _Pragma("unroll") for (int n = 0; n < 2; ++n) _Pragma("unroll") for (int k = 0; k < 2; ++k) dst[n][k] = *(const PG8_LAS bf16x8*)(lds + PG8_SB(b, h) + boff + n * 2048 + k * 1024); } while (0)
; #define PG8_MMA(ai, bj, At, Bt) do { __builtin_amdgcn_s_setprio(1); _Pragma("unroll") for (int m = 0; m < 4; ++m) _Pragma("unroll") for (int n = 0; n < 2; ++n) _Pragma("unroll") for (int k = 0; k < 2; ++k) \
;         acc[ai][bj][m][n] = __builtin_amdgcn_mfma_f32_16x16x32_bf16(Bt[n][k], At[m][k], acc[ai][bj][m][n], 0, 0, 0); __builtin_amdgcn_s_setprio(0); } while (0)
; #define PG8_WAIT_V(n) asm volatile("s_waitcnt vmcnt(" #n ")" ::: "memory")
; #define PG8_WAIT_L(n) asm volatile("s_waitcnt lgkmcnt(" #n ")" ::: "memory")
; #define PG8_BAR __builtin_amdgcn_s_barrier()
; #define PG8_SCHED __builtin_amdgcn_sched_barrier(0)
; template <class Epi, class Sched, bool ALIGN_EPI = false, bool SP2 = false>
; __device__ __forceinline__ void gemm_phase(PG8_LAS unsigned char* lds, const Gemm g, const Sched& S, const Epi& E) {
;     ...
;             PG8_LDB(B0, 0, 0); PG8_LDB(B1, 0, 1); PG8_SCHED; PG8_LDA(At, 0, 0); PG8_STAGE(PG8_SA(1, 1), a1 + hstep, voffA);
;             PG8_WAIT_V(8); PG8_WAIT_L(0); PG8_BAR; PG8_MMA(0, 0, At, B0); PG8_MMA(0, 1, At, B1); PG8_BAR; PG8_SCHED;
;             PG8_LDA(At, 0, 1); PG8_STAGE(PG8_SB(0, 0), b2, voffB); PG8_STAGE(PG8_SB(0, 1), b2 + hstep, voffB); PG8_STAGE(PG8_SA(0, 0), a2, voffA);
;             PG8_WAIT_V(8); PG8_WAIT_L(0); PG8_BAR; PG8_MMA(1, 0, At, B0); PG8_MMA(1, 1, At, B1); PG8_BAR; PG8_SCHED;
.LBB0_1540:
	ds_read_b128 v[142:145], v156
	ds_read_b128 v[146:149], v156 offset:1024
	ds_read_b128 v[160:163], v156 offset:2048
	ds_read_b128 v[164:167], v156 offset:3072
	ds_read_b128 v[172:175], v157
	s_waitcnt lgkmcnt(0)
	ds_read_b128 v[178:181], v157 offset:1024
	ds_read_b128 v[182:185], v157 offset:2048
	ds_read_b128 v[186:189], v157 offset:3072
	s_add_u32 s28, s26, 0xfffc0080
	s_addc_u32 s29, s27, -1
	s_cmp_eq_u32 s48, 12
	s_cselect_b32 s31, s23, s29
	s_cselect_b32 s30, s22, s28
	s_cselect_b32 s29, s25, s21
	s_cselect_b32 s28, s24, s19
	v_lshl_add_u64 v[168:169], s[26:27], 0, v[138:139]
	s_add_i32 m0, s37, 0xc000
	ds_read_b128 v[190:193], v158
	ds_read_b128 v[194:197], v158 offset:1024
	ds_read_b128 v[198:201], v158 offset:2048
	ds_read_b128 v[202:205], v158 offset:3072
	ds_read_b128 v[208:211], v158 offset:4096
	ds_read_b128 v[212:215], v158 offset:5120
	ds_read_b128 v[216:219], v158 offset:6144
	ds_read_b128 v[220:223], v158 offset:7168
	global_load_lds_dwordx4 v[168:169], off
	v_lshl_add_u64 v[168:169], s[26:27], 0, v[140:141]
	s_add_i32 m0, s37, 0xe000
	s_nop 0
	global_load_lds_dwordx4 v[168:169], off
	s_waitcnt vmcnt(8)
	s_waitcnt lgkmcnt(0)
	s_barrier
	s_setprio 1
	s_waitcnt lgkmcnt(0)
	v_mfma_f32_16x16x32_bf16 v[124:127], v[142:145], v[190:193], v[124:127]
	v_mfma_f32_16x16x32_bf16 v[120:123], v[160:163], v[190:193], v[120:123]
	v_mfma_f32_16x16x32_bf16 v[108:111], v[142:145], v[198:201], v[108:111]
	v_mfma_f32_16x16x32_bf16 v[104:107], v[160:163], v[198:201], v[104:107]
	v_mfma_f32_16x16x32_bf16 v[92:95], v[142:145], v[208:211], v[92:95]
	v_mfma_f32_16x16x32_bf16 v[88:91], v[160:163], v[208:211], v[88:91]
	v_mfma_f32_16x16x32_bf16 v[76:79], v[142:145], v[216:219], v[76:79]
	v_mfma_f32_16x16x32_bf16 v[72:75], v[160:163], v[216:219], v[72:75]
	v_mfma_f32_16x16x32_bf16 v[124:127], v[146:149], v[194:197], v[124:127]
	v_mfma_f32_16x16x32_bf16 v[120:123], v[164:167], v[194:197], v[120:123]
	v_mfma_f32_16x16x32_bf16 v[108:111], v[146:149], v[202:205], v[108:111]
	v_mfma_f32_16x16x32_bf16 v[104:107], v[164:167], v[202:205], v[104:107]
	v_mfma_f32_16x16x32_bf16 v[92:95], v[146:149], v[212:215], v[92:95]
	v_mfma_f32_16x16x32_bf16 v[88:91], v[164:167], v[212:215], v[88:91]
	v_mfma_f32_16x16x32_bf16 v[76:79], v[146:149], v[220:223], v[76:79]
	v_mfma_f32_16x16x32_bf16 v[72:75], v[164:167], v[220:223], v[72:75]
	s_setprio 0
	s_setprio 1
	v_mfma_f32_16x16x32_bf16 v[116:119], v[172:175], v[190:193], v[116:119]
	v_mfma_f32_16x16x32_bf16 v[112:115], v[182:185], v[190:193], v[112:115]
	v_mfma_f32_16x16x32_bf16 v[100:103], v[172:175], v[198:201], v[100:103]
	v_mfma_f32_16x16x32_bf16 v[96:99], v[182:185], v[198:201], v[96:99]
	v_mfma_f32_16x16x32_bf16 v[84:87], v[172:175], v[208:211], v[84:87]
	v_mfma_f32_16x16x32_bf16 v[80:83], v[182:185], v[208:211], v[80:83]
	v_mfma_f32_16x16x32_bf16 v[68:71], v[172:175], v[216:219], v[68:71]
	v_mfma_f32_16x16x32_bf16 v[64:67], v[182:185], v[216:219], v[64:67]
	v_mfma_f32_16x16x32_bf16 v[116:119], v[178:181], v[194:197], v[116:119]
	v_mfma_f32_16x16x32_bf16 v[112:115], v[186:189], v[194:197], v[112:115]
	v_mfma_f32_16x16x32_bf16 v[100:103], v[178:181], v[202:205], v[100:103]
	v_mfma_f32_16x16x32_bf16 v[96:99], v[186:189], v[202:205], v[96:99]
	v_mfma_f32_16x16x32_bf16 v[84:87], v[178:181], v[212:215], v[84:87]
	v_mfma_f32_16x16x32_bf16 v[80:83], v[186:189], v[212:215], v[80:83]
	v_mfma_f32_16x16x32_bf16 v[68:71], v[178:181], v[220:223], v[68:71]
	v_mfma_f32_16x16x32_bf16 v[64:67], v[186:189], v[220:223], v[64:67]
	s_setprio 0
	s_barrier
	s_add_i32 s49, s50, s36
	v_lshl_add_u64 v[168:169], s[28:29], 0, v[130:131]
	s_mov_b32 m0, s49
	ds_read_b128 v[190:193], v158 offset:16384
	ds_read_b128 v[194:197], v158 offset:17408
	ds_read_b128 v[198:201], v158 offset:18432
	ds_read_b128 v[202:205], v158 offset:19456
	ds_read_b128 v[208:211], v158 offset:20480
	ds_read_b128 v[212:215], v158 offset:21504
	ds_read_b128 v[216:219], v158 offset:22528
	ds_read_b128 v[220:223], v158 offset:23552
	global_load_lds_dwordx4 v[168:169], off
	s_add_i32 m0, s49, 0x2000
	s_add_u32 s52, s28, 0x40000
	v_lshl_add_u64 v[224:225], s[28:29], 0, v[134:135]
	s_addc_u32 s53, s29, 0
	s_add_i32 s49, s51, s36
	global_load_lds_dwordx4 v[224:225], off
	v_lshl_add_u64 v[226:227], s[52:53], 0, v[130:131]
	s_mov_b32 m0, s49
	v_lshl_add_u64 v[228:229], s[30:31], 0, v[132:133]
	global_load_lds_dwordx4 v[226:227], off
	v_lshl_add_u64 v[226:227], s[52:53], 0, v[134:135]
	s_add_i32 m0, s49, 0x2000
	s_nop 0
	global_load_lds_dwordx4 v[226:227], off
	v_lshl_add_u64 v[226:227], s[30:31], 0, v[128:129]
	s_mov_b32 m0, s37
	s_nop 0
	global_load_lds_dwordx4 v[226:227], off
	s_mov_b32 m0, s38
	s_nop 0
	global_load_lds_dwordx4 v[228:229], off
	s_waitcnt vmcnt(8)
	s_waitcnt lgkmcnt(0)
	s_barrier
; #define PG8_STAGE(bufoff, gbase, voff) do { _Pragma("unroll") for (int _i = 0; _i < 2; ++_i) \
;         __builtin_amdgcn_global_load_lds((const unsigned*)((const char*)(gbase) + (voff)[_i]), (PG8_LAS unsigned*)(lds + (bufoff) + ldsw + _i * 8192), 16, 0, 0); } while (0)
; #define PG8_LDA(dst, b, h) do { _Pragma("unroll") for (int m = 0; m < 4; ++m) _Pragma("unroll") for (int k = 0; k < 2; ++k) dst[m][k] = *(const PG8_LAS bf16x8*)(lds + PG8_SA(b, h) + aoff + m * 2048 + k * 1024); } while (0)
; #define PG8_LDB(dst, b, h) do { _Pragma("unroll") for (int n = 0; n < 2; ++n) _Pragma("unroll") for (int k = 0; k < 2; ++k) dst[n][k] = *(const PG8_LAS bf16x8*)(lds + PG8_SB(b, h) + boff + n * 2048 + k * 1024); } while (0)
; #define PG8_MMA(ai, bj, At, Bt) do { __builtin_amdgcn_s_setprio(1); _Pragma("unroll") for (int m = 0; m < 4; ++m) _Pragma("unroll") for (int n = 0; n < 2; ++n) _Pragma("unroll") for (int k = 0; k < 2; ++k) \
;         acc[ai][bj][m][n] = __builtin_amdgcn_mfma_f32_16x16x32_bf16(Bt[n][k], At[m][k], acc[ai][bj][m][n], 0, 0, 0); __builtin_amdgcn_s_setprio(0); } while (0)
; #define PG8_WAIT_V(n) asm volatile("s_waitcnt vmcnt(" #n ")" ::: "memory")
; #define PG8_WAIT_L(n) asm volatile("s_waitcnt lgkmcnt(" #n ")" ::: "memory")
; #define PG8_BAR __builtin_amdgcn_s_barrier()
; #define PG8_SCHED __builtin_amdgcn_sched_barrier(0)
; template <class Epi, class Sched, bool ALIGN_EPI = false, bool SP2 = false>
; __device__ __forceinline__ void gemm_phase(PG8_LAS unsigned char* lds, const Gemm g, const Sched& S, const Epi& E) {
;     ...
;             PG8_WAIT_V(8); PG8_WAIT_L(0); PG8_BAR; PG8_MMA(1, 0, At, B0); PG8_MMA(1, 1, At, B1); PG8_BAR; PG8_SCHED;
;             PG8_LDB(B0, 1, 0); PG8_LDB(B1, 1, 1); PG8_SCHED; PG8_LDA(At, 1, 0); PG8_STAGE(PG8_SA(0, 1), a2 + hstep, voffA);
;             PG8_WAIT_V(8); PG8_WAIT_L(0); PG8_BAR; PG8_MMA(0, 0, At, B0); PG8_MMA(0, 1, At, B1); PG8_BAR; PG8_SCHED;
;             PG8_LDA(At, 1, 1); PG8_STAGE(PG8_SB(1, 0), b3, voffB); PG8_STAGE(PG8_SB(1, 1), b3 + hstep, voffB); PG8_STAGE(PG8_SA(1, 0), a3, voffA);
	s_setprio 1
	s_waitcnt lgkmcnt(0)
	v_mfma_f32_16x16x32_bf16 v[60:63], v[142:145], v[190:193], v[60:63]
	v_mfma_f32_16x16x32_bf16 v[56:59], v[160:163], v[190:193], v[56:59]
	v_mfma_f32_16x16x32_bf16 v[44:47], v[142:145], v[198:201], v[44:47]
	v_mfma_f32_16x16x32_bf16 v[40:43], v[160:163], v[198:201], v[40:43]
	v_mfma_f32_16x16x32_bf16 v[28:31], v[142:145], v[208:211], v[28:31]
	v_mfma_f32_16x16x32_bf16 v[24:27], v[160:163], v[208:211], v[24:27]
	v_mfma_f32_16x16x32_bf16 v[12:15], v[142:145], v[216:219], v[12:15]
	v_mfma_f32_16x16x32_bf16 v[8:11], v[160:163], v[216:219], v[8:11]
	v_mfma_f32_16x16x32_bf16 v[60:63], v[146:149], v[194:197], v[60:63]
	v_mfma_f32_16x16x32_bf16 v[56:59], v[164:167], v[194:197], v[56:59]
	v_mfma_f32_16x16x32_bf16 v[44:47], v[146:149], v[202:205], v[44:47]
	v_mfma_f32_16x16x32_bf16 v[40:43], v[164:167], v[202:205], v[40:43]
	v_mfma_f32_16x16x32_bf16 v[28:31], v[146:149], v[212:215], v[28:31]
	v_mfma_f32_16x16x32_bf16 v[24:27], v[164:167], v[212:215], v[24:27]
	v_mfma_f32_16x16x32_bf16 v[12:15], v[146:149], v[220:223], v[12:15]
	v_mfma_f32_16x16x32_bf16 v[8:11], v[164:167], v[220:223], v[8:11]
	s_setprio 0
	s_setprio 1
	v_mfma_f32_16x16x32_bf16 v[52:55], v[172:175], v[190:193], v[52:55]
	v_mfma_f32_16x16x32_bf16 v[48:51], v[182:185], v[190:193], v[48:51]
	v_mfma_f32_16x16x32_bf16 v[36:39], v[172:175], v[198:201], v[36:39]
	v_mfma_f32_16x16x32_bf16 v[32:35], v[182:185], v[198:201], v[32:35]
	v_mfma_f32_16x16x32_bf16 v[20:23], v[172:175], v[208:211], v[20:23]
	v_mfma_f32_16x16x32_bf16 v[16:19], v[182:185], v[208:211], v[16:19]
	v_mfma_f32_16x16x32_bf16 v[4:7], v[172:175], v[216:219], v[4:7]
	v_mfma_f32_16x16x32_bf16 v[0:3], v[182:185], v[216:219], v[0:3]
	v_mfma_f32_16x16x32_bf16 v[52:55], v[178:181], v[194:197], v[52:55]
	v_mfma_f32_16x16x32_bf16 v[48:51], v[186:189], v[194:197], v[48:51]
	v_mfma_f32_16x16x32_bf16 v[36:39], v[178:181], v[202:205], v[36:39]
	v_mfma_f32_16x16x32_bf16 v[32:35], v[186:189], v[202:205], v[32:35]
	v_mfma_f32_16x16x32_bf16 v[20:23], v[178:181], v[212:215], v[20:23]
	v_mfma_f32_16x16x32_bf16 v[16:19], v[186:189], v[212:215], v[16:19]
	v_mfma_f32_16x16x32_bf16 v[4:7], v[178:181], v[220:223], v[4:7]
	v_mfma_f32_16x16x32_bf16 v[0:3], v[186:189], v[220:223], v[0:3]
	s_setprio 0
	s_barrier
	s_add_i32 s52, 0, 0x18000
	v_add_u32_e32 v136, s52, v151
	s_add_i32 s53, 0, 0x1c000
	ds_read_b128 v[142:145], v136
	ds_read_b128 v[146:149], v136 offset:1024
	ds_read_b128 v[160:163], v136 offset:2048
	ds_read_b128 v[164:167], v136 offset:3072
	v_add_u32_e32 v136, s53, v151
	ds_read_b128 v[172:175], v136
	ds_read_b128 v[178:181], v136 offset:1024
	ds_read_b128 v[182:185], v136 offset:2048
	ds_read_b128 v[186:189], v136 offset:3072
	s_add_u32 s30, s30, 0x40000
	s_addc_u32 s31, s31, 0
	s_mov_b32 m0, s39
	v_lshl_add_u64 v[230:231], s[30:31], 0, v[128:129]
	ds_read_b128 v[190:193], v158 offset:32768
	ds_read_b128 v[194:197], v158 offset:33792
	ds_read_b128 v[198:201], v158 offset:34816
	ds_read_b128 v[202:205], v158 offset:35840
	ds_read_b128 v[208:211], v158 offset:36864
	ds_read_b128 v[212:215], v158 offset:37888
	ds_read_b128 v[216:219], v158 offset:38912
	ds_read_b128 v[220:223], v158 offset:39936
	global_load_lds_dwordx4 v[230:231], off
	v_lshl_add_u64 v[230:231], s[30:31], 0, v[132:133]
	s_mov_b32 m0, s40
	s_nop 0
	global_load_lds_dwordx4 v[230:231], off
	s_waitcnt vmcnt(8)
	s_waitcnt lgkmcnt(0)
	s_barrier
	s_setprio 1
	s_waitcnt lgkmcnt(0)
	v_mfma_f32_16x16x32_bf16 v[124:127], v[142:145], v[190:193], v[124:127]
	v_mfma_f32_16x16x32_bf16 v[120:123], v[160:163], v[190:193], v[120:123]
	v_mfma_f32_16x16x32_bf16 v[108:111], v[142:145], v[198:201], v[108:111]
	v_mfma_f32_16x16x32_bf16 v[104:107], v[160:163], v[198:201], v[104:107]
	v_mfma_f32_16x16x32_bf16 v[92:95], v[142:145], v[208:211], v[92:95]
	v_mfma_f32_16x16x32_bf16 v[88:91], v[160:163], v[208:211], v[88:91]
	v_mfma_f32_16x16x32_bf16 v[76:79], v[142:145], v[216:219], v[76:79]
	v_mfma_f32_16x16x32_bf16 v[72:75], v[160:163], v[216:219], v[72:75]
	v_mfma_f32_16x16x32_bf16 v[124:127], v[146:149], v[194:197], v[124:127]
	v_mfma_f32_16x16x32_bf16 v[120:123], v[164:167], v[194:197], v[120:123]
	v_mfma_f32_16x16x32_bf16 v[108:111], v[146:149], v[202:205], v[108:111]
	v_mfma_f32_16x16x32_bf16 v[104:107], v[164:167], v[202:205], v[104:107]
	v_mfma_f32_16x16x32_bf16 v[92:95], v[146:149], v[212:215], v[92:95]
	v_mfma_f32_16x16x32_bf16 v[88:91], v[164:167], v[212:215], v[88:91]
	v_mfma_f32_16x16x32_bf16 v[76:79], v[146:149], v[220:223], v[76:79]
	v_mfma_f32_16x16x32_bf16 v[72:75], v[164:167], v[220:223], v[72:75]
	s_setprio 0
	s_setprio 1
	v_mfma_f32_16x16x32_bf16 v[116:119], v[172:175], v[190:193], v[116:119]
	v_mfma_f32_16x16x32_bf16 v[112:115], v[182:185], v[190:193], v[112:115]
	v_mfma_f32_16x16x32_bf16 v[100:103], v[172:175], v[198:201], v[100:103]
	v_mfma_f32_16x16x32_bf16 v[96:99], v[182:185], v[198:201], v[96:99]
	v_mfma_f32_16x16x32_bf16 v[84:87], v[172:175], v[208:211], v[84:87]
	v_mfma_f32_16x16x32_bf16 v[80:83], v[182:185], v[208:211], v[80:83]
	v_mfma_f32_16x16x32_bf16 v[68:71], v[172:175], v[216:219], v[68:71]
	v_mfma_f32_16x16x32_bf16 v[64:67], v[182:185], v[216:219], v[64:67]
	v_mfma_f32_16x16x32_bf16 v[116:119], v[178:181], v[194:197], v[116:119]
	v_mfma_f32_16x16x32_bf16 v[112:115], v[186:189], v[194:197], v[112:115]
	v_mfma_f32_16x16x32_bf16 v[100:103], v[178:181], v[202:205], v[100:103]
	v_mfma_f32_16x16x32_bf16 v[96:99], v[186:189], v[202:205], v[96:99]
	v_mfma_f32_16x16x32_bf16 v[84:87], v[178:181], v[212:215], v[84:87]
	v_mfma_f32_16x16x32_bf16 v[80:83], v[186:189], v[212:215], v[80:83]
	v_mfma_f32_16x16x32_bf16 v[68:71], v[178:181], v[220:223], v[68:71]
	v_mfma_f32_16x16x32_bf16 v[64:67], v[186:189], v[220:223], v[64:67]
	s_setprio 0
	s_barrier
; #define PG8_STAGE(bufoff, gbase, voff) do { _Pragma("unroll") for (int _i = 0; _i < 2; ++_i) \
;         __builtin_amdgcn_global_load_lds((const unsigned*)((const char*)(gbase) + (voff)[_i]), (PG8_LAS unsigned*)(lds + (bufoff) + ldsw + _i * 8192), 16, 0, 0); } while (0)
; #define PG8_LDA(dst, b, h) do { _Pragma("unroll") for (int m = 0; m < 4; ++m) _Pragma("unroll") for (int k = 0; k < 2; ++k) dst[m][k] = *(const PG8_LAS bf16x8*)(lds + PG8_SA(b, h) + aoff + m * 2048 + k * 1024); } while (0)
; #define PG8_MMA(ai, bj, At, Bt) do { __builtin_amdgcn_s_setprio(1); _Pragma("unroll") for (int m = 0; m < 4; ++m) _Pragma("unroll") for (int n = 0; n < 2; ++n) _Pragma("unroll") for (int k = 0; k < 2; ++k) \
;         acc[ai][bj][m][n] = __builtin_amdgcn_mfma_f32_16x16x32_bf16(Bt[n][k], At[m][k], acc[ai][bj][m][n], 0, 0, 0); __builtin_amdgcn_s_setprio(0); } while (0)
; #define PG8_WAIT_V(n) asm volatile("s_waitcnt vmcnt(" #n ")" ::: "memory")
; #define PG8_WAIT_L(n) asm volatile("s_waitcnt lgkmcnt(" #n ")" ::: "memory")
; #define PG8_BAR __builtin_amdgcn_s_barrier()
; #define PG8_SCHED __builtin_amdgcn_sched_barrier(0)
; template <class Epi, class Sched, bool ALIGN_EPI = false, bool SP2 = false>
; __device__ __forceinline__ void gemm_phase(PG8_LAS unsigned char* lds, const Gemm g, const Sched& S, const Epi& E) {
;     ...
;         for (int t = 0; t < nt; t += 2) {
;     ...
;             PG8_LDA(At, 1, 1); PG8_STAGE(PG8_SB(1, 0), b3, voffB); PG8_STAGE(PG8_SB(1, 1), b3 + hstep, voffB); PG8_STAGE(PG8_SA(1, 0), a3, voffA);
;             PG8_WAIT_V(8); PG8_WAIT_L(0); PG8_BAR; PG8_MMA(1, 0, At, B0); PG8_MMA(1, 1, At, B1); PG8_BAR; PG8_SCHED;
	s_add_i32 s30, s52, s36
	v_lshl_add_u64 v[168:169], v[168:169], 0, s[14:15]
	s_mov_b32 m0, s30
	ds_read_b128 v[190:193], v158 offset:49152
	ds_read_b128 v[194:197], v158 offset:50176
	ds_read_b128 v[198:201], v158 offset:51200
	ds_read_b128 v[202:205], v158 offset:52224
	ds_read_b128 v[208:211], v158 offset:53248
	ds_read_b128 v[212:215], v158 offset:54272
	ds_read_b128 v[216:219], v158 offset:55296
	ds_read_b128 v[220:223], v158 offset:56320
	global_load_lds_dwordx4 v[168:169], off
	s_add_i32 m0, s30, 0x2000
	s_add_u32 s28, s28, 0x40080
	v_lshl_add_u64 v[168:169], v[224:225], 0, s[14:15]
	s_addc_u32 s29, s29, 0
	s_add_i32 s30, s53, s36
	global_load_lds_dwordx4 v[168:169], off
	v_lshl_add_u64 v[168:169], s[28:29], 0, v[130:131]
	s_mov_b32 m0, s30
	s_nop 0
	global_load_lds_dwordx4 v[168:169], off
	v_lshl_add_u64 v[168:169], s[28:29], 0, v[134:135]
	s_add_i32 m0, s30, 0x2000
	s_nop 0
	global_load_lds_dwordx4 v[168:169], off
	v_lshl_add_u64 v[168:169], v[226:227], 0, s[14:15]
	s_mov_b32 m0, s42
	s_nop 0
	global_load_lds_dwordx4 v[168:169], off
	v_lshl_add_u64 v[168:169], v[228:229], 0, s[14:15]
	s_mov_b32 m0, s43
	s_nop 0
	global_load_lds_dwordx4 v[168:169], off
	s_waitcnt vmcnt(8)
	s_waitcnt lgkmcnt(0)
	s_barrier
	s_setprio 1
	s_waitcnt lgkmcnt(0)
	v_mfma_f32_16x16x32_bf16 v[60:63], v[142:145], v[190:193], v[60:63]
	v_mfma_f32_16x16x32_bf16 v[56:59], v[160:163], v[190:193], v[56:59]
	v_mfma_f32_16x16x32_bf16 v[44:47], v[142:145], v[198:201], v[44:47]
	v_mfma_f32_16x16x32_bf16 v[40:43], v[160:163], v[198:201], v[40:43]
	v_mfma_f32_16x16x32_bf16 v[28:31], v[142:145], v[208:211], v[28:31]
	v_mfma_f32_16x16x32_bf16 v[24:27], v[160:163], v[208:211], v[24:27]
	v_mfma_f32_16x16x32_bf16 v[12:15], v[142:145], v[216:219], v[12:15]
	v_mfma_f32_16x16x32_bf16 v[8:11], v[160:163], v[216:219], v[8:11]
	v_mfma_f32_16x16x32_bf16 v[60:63], v[146:149], v[194:197], v[60:63]
	v_mfma_f32_16x16x32_bf16 v[56:59], v[164:167], v[194:197], v[56:59]
	v_mfma_f32_16x16x32_bf16 v[44:47], v[146:149], v[202:205], v[44:47]
	v_mfma_f32_16x16x32_bf16 v[40:43], v[164:167], v[202:205], v[40:43]
	v_mfma_f32_16x16x32_bf16 v[28:31], v[146:149], v[212:215], v[28:31]
	v_mfma_f32_16x16x32_bf16 v[24:27], v[164:167], v[212:215], v[24:27]
	v_mfma_f32_16x16x32_bf16 v[12:15], v[146:149], v[220:223], v[12:15]
	v_mfma_f32_16x16x32_bf16 v[8:11], v[164:167], v[220:223], v[8:11]
	s_setprio 0
	s_setprio 1
	v_mfma_f32_16x16x32_bf16 v[52:55], v[172:175], v[190:193], v[52:55]
	v_mfma_f32_16x16x32_bf16 v[48:51], v[182:185], v[190:193], v[48:51]
	v_mfma_f32_16x16x32_bf16 v[36:39], v[172:175], v[198:201], v[36:39]
	v_mfma_f32_16x16x32_bf16 v[32:35], v[182:185], v[198:201], v[32:35]
	v_mfma_f32_16x16x32_bf16 v[20:23], v[172:175], v[208:211], v[20:23]
	v_mfma_f32_16x16x32_bf16 v[16:19], v[182:185], v[208:211], v[16:19]
	v_mfma_f32_16x16x32_bf16 v[4:7], v[172:175], v[216:219], v[4:7]
	v_mfma_f32_16x16x32_bf16 v[0:3], v[182:185], v[216:219], v[0:3]
	v_mfma_f32_16x16x32_bf16 v[52:55], v[178:181], v[194:197], v[52:55]
	v_mfma_f32_16x16x32_bf16 v[48:51], v[186:189], v[194:197], v[48:51]
	v_mfma_f32_16x16x32_bf16 v[36:39], v[178:181], v[202:205], v[36:39]
	v_mfma_f32_16x16x32_bf16 v[32:35], v[186:189], v[202:205], v[32:35]
	v_mfma_f32_16x16x32_bf16 v[20:23], v[178:181], v[212:215], v[20:23]
	v_mfma_f32_16x16x32_bf16 v[16:19], v[186:189], v[212:215], v[16:19]
	v_mfma_f32_16x16x32_bf16 v[4:7], v[178:181], v[220:223], v[4:7]
	v_mfma_f32_16x16x32_bf16 v[0:3], v[186:189], v[220:223], v[0:3]
	s_setprio 0
	s_add_i32 s48, s48, 2
	s_add_u32 s26, s26, 0x100
	s_addc_u32 s27, s27, 0
	s_add_u32 s19, s19, 0x100
	s_addc_u32 s21, s21, 0
	s_cmp_gt_u32 s48, 13
	s_barrier
	s_cbranch_scc0 .LBB0_1540
	s_and_b64 vcc, exec, s[16:17]
	s_cbranch_vccz .LBB0_1543
	s_barrier

; #define PG8_STAGE(bufoff, gbase, voff) do { _Pragma("unroll") for (int _i = 0; _i < 2; ++_i) \
;         __builtin_amdgcn_global_load_lds((const unsigned*)((const char*)(gbase) + (voff)[_i]), (PG8_LAS unsigned*)(lds + (bufoff) + ldsw + _i * 8192), 16, 0, 0); } while (0)
; #define PG8_LDA(dst, b, h) do { _Pragma("unroll") for (int m = 0; m < 4; ++m) _Pragma("unroll") for (int k = 0; k < 2; ++k) dst[m][k] = *(const PG8_LAS bf16x8*)(lds + PG8_SA(b, h) + aoff + m * 2048 + k * 1024); } while (0)
; #define PG8_LDB(dst, b, h) do { _Pragma("unroll") for (int n = 0; n < 2; ++n) _Pragma("unroll") for (int k = 0; k < 2; ++k) dst[n][k] = *(const PG8_LAS bf16x8*)(lds + PG8_SB(b, h) + boff + n * 2048 + k * 1024); } while (0)
; #define PG8_MMA(ai, bj, At, Bt) do { __builtin_amdgcn_s_setprio(1); _Pragma("unroll") for (int m = 0; m < 4; ++m) _Pragma("unroll") for (int n = 0; n < 2; ++n) _Pragma("unroll") for (int k = 0; k < 2; ++k) \
;         acc[ai][bj][m][n] = __builtin_amdgcn_mfma_f32_16x16x32_bf16(Bt[n][k], At[m][k], acc[ai][bj][m][n], 0, 0, 0); __builtin_amdgcn_s_setprio(0); } while (0)
; #define PG8_WAIT_V(n) asm volatile("s_waitcnt vmcnt(" #n ")" ::: "memory")
; #define PG8_WAIT_L(n) asm volatile("s_waitcnt lgkmcnt(" #n ")" ::: "memory")
; #define PG8_BAR __builtin_amdgcn_s_barrier()
; #define PG8_SCHED __builtin_amdgcn_sched_barrier(0)
; template <class Epi, class Sched, bool ALIGN_EPI = false, bool SP2 = false>
; __device__ __forceinline__ void gemm_phase(PG8_LAS unsigned char* lds, const Gemm g, const Sched& S, const Epi& E) {
;     ...
;             PG8_LDB(B0, 0, 0); PG8_LDB(B1, 0, 1); PG8_SCHED; PG8_LDA(At, 0, 0); PG8_STAGE(PG8_SA(1, 1), a1 + hstep, voffA);
;             PG8_WAIT_V(8); PG8_WAIT_L(0); PG8_BAR; PG8_MMA(0, 0, At, B0); PG8_MMA(0, 1, At, B1); PG8_BAR; PG8_SCHED;
;             PG8_LDA(At, 0, 1); PG8_STAGE(PG8_SB(0, 0), b2, voffB); PG8_STAGE(PG8_SB(0, 1), b2 + hstep, voffB); PG8_STAGE(PG8_SA(0, 0), a2, voffA);
;             PG8_WAIT_V(8); PG8_WAIT_L(0); PG8_BAR; PG8_MMA(1, 0, At, B0); PG8_MMA(1, 1, At, B1); PG8_BAR; PG8_SCHED;
.LBB0_1604:
	ds_read_b128 v[140:143], v150
	ds_read_b128 v[154:157], v150 offset:1024
	ds_read_b128 v[158:161], v150 offset:2048
	ds_read_b128 v[162:165], v150 offset:3072
	ds_read_b128 v[166:169], v151
	ds_read_b128 v[172:175], v151 offset:1024
	ds_read_b128 v[178:181], v151 offset:2048
	ds_read_b128 v[182:185], v151 offset:3072
	s_add_u32 s34, s30, 0xfffc0080
	s_addc_u32 s35, s31, -1
	s_cmp_eq_u32 s49, 12
	s_cselect_b32 s37, s21, s35
	s_cselect_b32 s36, s45, s34
	s_cselect_b32 s35, s23, s48
	s_cselect_b32 s34, s46, s47
	v_lshl_add_u64 v[220:221], s[30:31], 0, v[136:137]
	s_add_i32 m0, s29, 0xc000
	ds_read_b128 v[186:189], v152
	ds_read_b128 v[190:193], v152 offset:1024
	ds_read_b128 v[194:197], v152 offset:2048
	ds_read_b128 v[198:201], v152 offset:3072
	ds_read_b128 v[202:205], v152 offset:4096
	ds_read_b128 v[208:211], v152 offset:5120
	ds_read_b128 v[212:215], v152 offset:6144
	ds_read_b128 v[216:219], v152 offset:7168
	global_load_lds_dwordx4 v[220:221], off
	v_lshl_add_u64 v[220:221], s[30:31], 0, v[138:139]
	s_add_i32 m0, s29, 0xe000
	s_nop 0
	global_load_lds_dwordx4 v[220:221], off
	s_waitcnt vmcnt(8)
	s_waitcnt lgkmcnt(0)
	s_barrier
	s_setprio 1
	s_waitcnt lgkmcnt(0)
	v_mfma_f32_16x16x32_bf16 v[124:127], v[140:143], v[186:189], v[124:127]
	v_mfma_f32_16x16x32_bf16 v[120:123], v[158:161], v[186:189], v[120:123]
	v_mfma_f32_16x16x32_bf16 v[108:111], v[140:143], v[194:197], v[108:111]
	v_mfma_f32_16x16x32_bf16 v[104:107], v[158:161], v[194:197], v[104:107]
	v_mfma_f32_16x16x32_bf16 v[92:95], v[140:143], v[202:205], v[92:95]
	v_mfma_f32_16x16x32_bf16 v[88:91], v[158:161], v[202:205], v[88:91]
	v_mfma_f32_16x16x32_bf16 v[76:79], v[140:143], v[212:215], v[76:79]
	v_mfma_f32_16x16x32_bf16 v[72:75], v[158:161], v[212:215], v[72:75]
	v_mfma_f32_16x16x32_bf16 v[124:127], v[154:157], v[190:193], v[124:127]
	v_mfma_f32_16x16x32_bf16 v[120:123], v[162:165], v[190:193], v[120:123]
	v_mfma_f32_16x16x32_bf16 v[108:111], v[154:157], v[198:201], v[108:111]
	v_mfma_f32_16x16x32_bf16 v[104:107], v[162:165], v[198:201], v[104:107]
	v_mfma_f32_16x16x32_bf16 v[92:95], v[154:157], v[208:211], v[92:95]
	v_mfma_f32_16x16x32_bf16 v[88:91], v[162:165], v[208:211], v[88:91]
	v_mfma_f32_16x16x32_bf16 v[76:79], v[154:157], v[216:219], v[76:79]
	v_mfma_f32_16x16x32_bf16 v[72:75], v[162:165], v[216:219], v[72:75]
	s_setprio 0
	s_setprio 1
	v_mfma_f32_16x16x32_bf16 v[116:119], v[166:169], v[186:189], v[116:119]
	v_mfma_f32_16x16x32_bf16 v[112:115], v[178:181], v[186:189], v[112:115]
	v_mfma_f32_16x16x32_bf16 v[100:103], v[166:169], v[194:197], v[100:103]
	v_mfma_f32_16x16x32_bf16 v[96:99], v[178:181], v[194:197], v[96:99]
	v_mfma_f32_16x16x32_bf16 v[84:87], v[166:169], v[202:205], v[84:87]
	v_mfma_f32_16x16x32_bf16 v[80:83], v[178:181], v[202:205], v[80:83]
	v_mfma_f32_16x16x32_bf16 v[68:71], v[166:169], v[212:215], v[68:71]
	v_mfma_f32_16x16x32_bf16 v[64:67], v[178:181], v[212:215], v[64:67]
	v_mfma_f32_16x16x32_bf16 v[116:119], v[172:175], v[190:193], v[116:119]
	v_mfma_f32_16x16x32_bf16 v[112:115], v[182:185], v[190:193], v[112:115]
	v_mfma_f32_16x16x32_bf16 v[100:103], v[172:175], v[198:201], v[100:103]
	v_mfma_f32_16x16x32_bf16 v[96:99], v[182:185], v[198:201], v[96:99]
	v_mfma_f32_16x16x32_bf16 v[84:87], v[172:175], v[208:211], v[84:87]
	v_mfma_f32_16x16x32_bf16 v[80:83], v[182:185], v[208:211], v[80:83]
	v_mfma_f32_16x16x32_bf16 v[68:71], v[172:175], v[216:219], v[68:71]
	v_mfma_f32_16x16x32_bf16 v[64:67], v[182:185], v[216:219], v[64:67]
	s_setprio 0
	s_barrier
	s_add_i32 s54, s50, s38
	v_lshl_add_u64 v[220:221], s[34:35], 0, v[132:133]
	s_mov_b32 m0, s54
	ds_read_b128 v[186:189], v152 offset:16384
	ds_read_b128 v[190:193], v152 offset:17408
	ds_read_b128 v[194:197], v152 offset:18432
	ds_read_b128 v[198:201], v152 offset:19456
	ds_read_b128 v[202:205], v152 offset:20480
	ds_read_b128 v[208:211], v152 offset:21504
	ds_read_b128 v[212:215], v152 offset:22528
	ds_read_b128 v[216:219], v152 offset:23552
	global_load_lds_dwordx4 v[220:221], off
	s_add_i32 m0, s54, 0x2000
	s_add_u32 s54, s34, 0x40000
	v_lshl_add_u64 v[222:223], s[34:35], 0, v[128:129]
	s_addc_u32 s55, s35, 0
	s_add_i32 s56, s51, s38
	global_load_lds_dwordx4 v[222:223], off
	v_lshl_add_u64 v[224:225], s[54:55], 0, v[132:133]
	s_mov_b32 m0, s56
	v_lshl_add_u64 v[226:227], s[36:37], 0, v[130:131]
	global_load_lds_dwordx4 v[224:225], off
	v_lshl_add_u64 v[224:225], s[54:55], 0, v[128:129]
	s_add_i32 m0, s56, 0x2000
	s_nop 0
	global_load_lds_dwordx4 v[224:225], off
	v_lshl_add_u64 v[224:225], s[36:37], 0, v[134:135]
	s_mov_b32 m0, s29
	s_nop 0
	global_load_lds_dwordx4 v[224:225], off
	s_mov_b32 m0, s39
	s_nop 0
	global_load_lds_dwordx4 v[226:227], off
	s_waitcnt vmcnt(8)
	s_waitcnt lgkmcnt(0)
	s_barrier
; #define PG8_STAGE(bufoff, gbase, voff) do { _Pragma("unroll") for (int _i = 0; _i < 2; ++_i) \
;         __builtin_amdgcn_global_load_lds((const unsigned*)((const char*)(gbase) + (voff)[_i]), (PG8_LAS unsigned*)(lds + (bufoff) + ldsw + _i * 8192), 16, 0, 0); } while (0)
; #define PG8_LDA(dst, b, h) do { _Pragma("unroll") for (int m = 0; m < 4; ++m) _Pragma("unroll") for (int k = 0; k < 2; ++k) dst[m][k] = *(const PG8_LAS bf16x8*)(lds + PG8_SA(b, h) + aoff + m * 2048 + k * 1024); } while (0)
; #define PG8_LDB(dst, b, h) do { _Pragma("unroll") for (int n = 0; n < 2; ++n) _Pragma("unroll") for (int k = 0; k < 2; ++k) dst[n][k] = *(const PG8_LAS bf16x8*)(lds + PG8_SB(b, h) + boff + n * 2048 + k * 1024); } while (0)
; #define PG8_MMA(ai, bj, At, Bt) do { __builtin_amdgcn_s_setprio(1); _Pragma("unroll") for (int m = 0; m < 4; ++m) _Pragma("unroll") for (int n = 0; n < 2; ++n) _Pragma("unroll") for (int k = 0; k < 2; ++k) \
;         acc[ai][bj][m][n] = __builtin_amdgcn_mfma_f32_16x16x32_bf16(Bt[n][k], At[m][k], acc[ai][bj][m][n], 0, 0, 0); __builtin_amdgcn_s_setprio(0); } while (0)
; #define PG8_WAIT_V(n) asm volatile("s_waitcnt vmcnt(" #n ")" ::: "memory")
; #define PG8_WAIT_L(n) asm volatile("s_waitcnt lgkmcnt(" #n ")" ::: "memory")
; #define PG8_BAR __builtin_amdgcn_s_barrier()
; #define PG8_SCHED __builtin_amdgcn_sched_barrier(0)
; template <class Epi, class Sched, bool ALIGN_EPI = false, bool SP2 = false>
; __device__ __forceinline__ void gemm_phase(PG8_LAS unsigned char* lds, const Gemm g, const Sched& S, const Epi& E) {
;     ...
;             PG8_WAIT_V(8); PG8_WAIT_L(0); PG8_BAR; PG8_MMA(1, 0, At, B0); PG8_MMA(1, 1, At, B1); PG8_BAR; PG8_SCHED;
;             PG8_LDB(B0, 1, 0); PG8_LDB(B1, 1, 1); PG8_SCHED; PG8_LDA(At, 1, 0); PG8_STAGE(PG8_SA(0, 1), a2 + hstep, voffA);
;             PG8_WAIT_V(8); PG8_WAIT_L(0); PG8_BAR; PG8_MMA(0, 0, At, B0); PG8_MMA(0, 1, At, B1); PG8_BAR; PG8_SCHED;
;             PG8_LDA(At, 1, 1); PG8_STAGE(PG8_SB(1, 0), b3, voffB); PG8_STAGE(PG8_SB(1, 1), b3 + hstep, voffB); PG8_STAGE(PG8_SA(1, 0), a3, voffA);
	s_setprio 1
	s_waitcnt lgkmcnt(0)
	v_mfma_f32_16x16x32_bf16 v[60:63], v[140:143], v[186:189], v[60:63]
	v_mfma_f32_16x16x32_bf16 v[56:59], v[158:161], v[186:189], v[56:59]
	v_mfma_f32_16x16x32_bf16 v[44:47], v[140:143], v[194:197], v[44:47]
	v_mfma_f32_16x16x32_bf16 v[40:43], v[158:161], v[194:197], v[40:43]
	v_mfma_f32_16x16x32_bf16 v[28:31], v[140:143], v[202:205], v[28:31]
	v_mfma_f32_16x16x32_bf16 v[24:27], v[158:161], v[202:205], v[24:27]
	v_mfma_f32_16x16x32_bf16 v[12:15], v[140:143], v[212:215], v[12:15]
	v_mfma_f32_16x16x32_bf16 v[8:11], v[158:161], v[212:215], v[8:11]
	v_mfma_f32_16x16x32_bf16 v[60:63], v[154:157], v[190:193], v[60:63]
	v_mfma_f32_16x16x32_bf16 v[56:59], v[162:165], v[190:193], v[56:59]
	v_mfma_f32_16x16x32_bf16 v[44:47], v[154:157], v[198:201], v[44:47]
	v_mfma_f32_16x16x32_bf16 v[40:43], v[162:165], v[198:201], v[40:43]
	v_mfma_f32_16x16x32_bf16 v[28:31], v[154:157], v[208:211], v[28:31]
	v_mfma_f32_16x16x32_bf16 v[24:27], v[162:165], v[208:211], v[24:27]
	v_mfma_f32_16x16x32_bf16 v[12:15], v[154:157], v[216:219], v[12:15]
	v_mfma_f32_16x16x32_bf16 v[8:11], v[162:165], v[216:219], v[8:11]
	s_setprio 0
	s_setprio 1
	v_mfma_f32_16x16x32_bf16 v[52:55], v[166:169], v[186:189], v[52:55]
	v_mfma_f32_16x16x32_bf16 v[48:51], v[178:181], v[186:189], v[48:51]
	v_mfma_f32_16x16x32_bf16 v[36:39], v[166:169], v[194:197], v[36:39]
	v_mfma_f32_16x16x32_bf16 v[32:35], v[178:181], v[194:197], v[32:35]
	v_mfma_f32_16x16x32_bf16 v[20:23], v[166:169], v[202:205], v[20:23]
	v_mfma_f32_16x16x32_bf16 v[16:19], v[178:181], v[202:205], v[16:19]
	v_mfma_f32_16x16x32_bf16 v[4:7], v[166:169], v[212:215], v[4:7]
	v_mfma_f32_16x16x32_bf16 v[0:3], v[178:181], v[212:215], v[0:3]
	v_mfma_f32_16x16x32_bf16 v[52:55], v[172:175], v[190:193], v[52:55]
	v_mfma_f32_16x16x32_bf16 v[48:51], v[182:185], v[190:193], v[48:51]
	v_mfma_f32_16x16x32_bf16 v[36:39], v[172:175], v[198:201], v[36:39]
	v_mfma_f32_16x16x32_bf16 v[32:35], v[182:185], v[198:201], v[32:35]
	v_mfma_f32_16x16x32_bf16 v[20:23], v[172:175], v[208:211], v[20:23]
	v_mfma_f32_16x16x32_bf16 v[16:19], v[182:185], v[208:211], v[16:19]
	v_mfma_f32_16x16x32_bf16 v[4:7], v[172:175], v[216:219], v[4:7]
	v_mfma_f32_16x16x32_bf16 v[0:3], v[182:185], v[216:219], v[0:3]
	s_setprio 0
	s_barrier
	v_add_u32_e32 v162, s52, v145
	v_add_u32_e32 v171, s53, v145
	ds_read_b128 v[140:143], v162
	ds_read_b128 v[154:157], v162 offset:1024
	ds_read_b128 v[158:161], v162 offset:2048
	ds_read_b128 v[162:165], v162 offset:3072
	ds_read_b128 v[166:169], v171
	ds_read_b128 v[172:175], v171 offset:1024
	ds_read_b128 v[178:181], v171 offset:2048
	ds_read_b128 v[182:185], v171 offset:3072
	s_add_u32 s36, s36, 0x40000
	s_addc_u32 s37, s37, 0
	s_mov_b32 m0, s40
	v_lshl_add_u64 v[228:229], s[36:37], 0, v[134:135]
	ds_read_b128 v[186:189], v152 offset:32768
	ds_read_b128 v[190:193], v152 offset:33792
	ds_read_b128 v[194:197], v152 offset:34816
	ds_read_b128 v[198:201], v152 offset:35840
	ds_read_b128 v[202:205], v152 offset:36864
	ds_read_b128 v[208:211], v152 offset:37888
	ds_read_b128 v[212:215], v152 offset:38912
	ds_read_b128 v[216:219], v152 offset:39936
	global_load_lds_dwordx4 v[228:229], off
	v_lshl_add_u64 v[228:229], s[36:37], 0, v[130:131]
	s_mov_b32 m0, s41
	s_nop 0
	global_load_lds_dwordx4 v[228:229], off
	s_waitcnt vmcnt(8)
	s_waitcnt lgkmcnt(0)
	s_barrier
	s_setprio 1
	s_waitcnt lgkmcnt(0)
	v_mfma_f32_16x16x32_bf16 v[124:127], v[140:143], v[186:189], v[124:127]
	v_mfma_f32_16x16x32_bf16 v[120:123], v[158:161], v[186:189], v[120:123]
	v_mfma_f32_16x16x32_bf16 v[108:111], v[140:143], v[194:197], v[108:111]
	v_mfma_f32_16x16x32_bf16 v[104:107], v[158:161], v[194:197], v[104:107]
	v_mfma_f32_16x16x32_bf16 v[92:95], v[140:143], v[202:205], v[92:95]
	v_mfma_f32_16x16x32_bf16 v[88:91], v[158:161], v[202:205], v[88:91]
	v_mfma_f32_16x16x32_bf16 v[76:79], v[140:143], v[212:215], v[76:79]
	v_mfma_f32_16x16x32_bf16 v[72:75], v[158:161], v[212:215], v[72:75]
	v_mfma_f32_16x16x32_bf16 v[124:127], v[154:157], v[190:193], v[124:127]
	v_mfma_f32_16x16x32_bf16 v[120:123], v[162:165], v[190:193], v[120:123]
	v_mfma_f32_16x16x32_bf16 v[108:111], v[154:157], v[198:201], v[108:111]
	v_mfma_f32_16x16x32_bf16 v[104:107], v[162:165], v[198:201], v[104:107]
	v_mfma_f32_16x16x32_bf16 v[92:95], v[154:157], v[208:211], v[92:95]
	v_mfma_f32_16x16x32_bf16 v[88:91], v[162:165], v[208:211], v[88:91]
	v_mfma_f32_16x16x32_bf16 v[76:79], v[154:157], v[216:219], v[76:79]
	v_mfma_f32_16x16x32_bf16 v[72:75], v[162:165], v[216:219], v[72:75]
	s_setprio 0
	s_setprio 1
	v_mfma_f32_16x16x32_bf16 v[116:119], v[166:169], v[186:189], v[116:119]
	v_mfma_f32_16x16x32_bf16 v[112:115], v[178:181], v[186:189], v[112:115]
	v_mfma_f32_16x16x32_bf16 v[100:103], v[166:169], v[194:197], v[100:103]
	v_mfma_f32_16x16x32_bf16 v[96:99], v[178:181], v[194:197], v[96:99]
	v_mfma_f32_16x16x32_bf16 v[84:87], v[166:169], v[202:205], v[84:87]
	v_mfma_f32_16x16x32_bf16 v[80:83], v[178:181], v[202:205], v[80:83]
	v_mfma_f32_16x16x32_bf16 v[68:71], v[166:169], v[212:215], v[68:71]
	v_mfma_f32_16x16x32_bf16 v[64:67], v[178:181], v[212:215], v[64:67]
	v_mfma_f32_16x16x32_bf16 v[116:119], v[172:175], v[190:193], v[116:119]
	v_mfma_f32_16x16x32_bf16 v[112:115], v[182:185], v[190:193], v[112:115]
	v_mfma_f32_16x16x32_bf16 v[100:103], v[172:175], v[198:201], v[100:103]
	v_mfma_f32_16x16x32_bf16 v[96:99], v[182:185], v[198:201], v[96:99]
	v_mfma_f32_16x16x32_bf16 v[84:87], v[172:175], v[208:211], v[84:87]
	v_mfma_f32_16x16x32_bf16 v[80:83], v[182:185], v[208:211], v[80:83]
	v_mfma_f32_16x16x32_bf16 v[68:71], v[172:175], v[216:219], v[68:71]
	v_mfma_f32_16x16x32_bf16 v[64:67], v[182:185], v[216:219], v[64:67]
	s_setprio 0
	s_barrier
; #define PG8_STAGE(bufoff, gbase, voff) do { _Pragma("unroll") for (int _i = 0; _i < 2; ++_i) \
;         __builtin_amdgcn_global_load_lds((const unsigned*)((const char*)(gbase) + (voff)[_i]), (PG8_LAS unsigned*)(lds + (bufoff) + ldsw + _i * 8192), 16, 0, 0); } while (0)
; #define PG8_LDA(dst, b, h) do { _Pragma("unroll") for (int m = 0; m < 4; ++m) _Pragma("unroll") for (int k = 0; k < 2; ++k) dst[m][k] = *(const PG8_LAS bf16x8*)(lds + PG8_SA(b, h) + aoff + m * 2048 + k * 1024); } while (0)
; #define PG8_MMA(ai, bj, At, Bt) do { __builtin_amdgcn_s_setprio(1); _Pragma("unroll") for (int m = 0; m < 4; ++m) _Pragma("unroll") for (int n = 0; n < 2; ++n) _Pragma("unroll") for (int k = 0; k < 2; ++k) \
;         acc[ai][bj][m][n] = __builtin_amdgcn_mfma_f32_16x16x32_bf16(Bt[n][k], At[m][k], acc[ai][bj][m][n], 0, 0, 0); __builtin_amdgcn_s_setprio(0); } while (0)
; #define PG8_WAIT_V(n) asm volatile("s_waitcnt vmcnt(" #n ")" ::: "memory")
; #define PG8_WAIT_L(n) asm volatile("s_waitcnt lgkmcnt(" #n ")" ::: "memory")
; #define PG8_BAR __builtin_amdgcn_s_barrier()
; #define PG8_SCHED __builtin_amdgcn_sched_barrier(0)
; template <class Epi, class Sched, bool ALIGN_EPI = false, bool SP2 = false>
; __device__ __forceinline__ void gemm_phase(PG8_LAS unsigned char* lds, const Gemm g, const Sched& S, const Epi& E) {
;     ...
;         for (int t = 0; t < nt; t += 2) {
;     ...
;             PG8_LDA(At, 1, 1); PG8_STAGE(PG8_SB(1, 0), b3, voffB); PG8_STAGE(PG8_SB(1, 1), b3 + hstep, voffB); PG8_STAGE(PG8_SA(1, 0), a3, voffA);
;             PG8_WAIT_V(8); PG8_WAIT_L(0); PG8_BAR; PG8_MMA(1, 0, At, B0); PG8_MMA(1, 1, At, B1); PG8_BAR; PG8_SCHED;
	s_add_i32 s36, s52, s38
	v_lshl_add_u64 v[220:221], v[220:221], 0, s[16:17]
	s_mov_b32 m0, s36
	ds_read_b128 v[186:189], v152 offset:49152
	ds_read_b128 v[190:193], v152 offset:50176
	ds_read_b128 v[194:197], v152 offset:51200
	ds_read_b128 v[198:201], v152 offset:52224
	ds_read_b128 v[202:205], v152 offset:53248
	ds_read_b128 v[208:211], v152 offset:54272
	ds_read_b128 v[212:215], v152 offset:55296
	ds_read_b128 v[216:219], v152 offset:56320
	global_load_lds_dwordx4 v[220:221], off
	s_add_i32 m0, s36, 0x2000
	s_add_u32 s34, s34, 0x40080
	v_lshl_add_u64 v[220:221], v[222:223], 0, s[16:17]
	s_addc_u32 s35, s35, 0
	s_add_i32 s36, s53, s38
	global_load_lds_dwordx4 v[220:221], off
	v_lshl_add_u64 v[220:221], s[34:35], 0, v[132:133]
	s_mov_b32 m0, s36
	s_nop 0
	global_load_lds_dwordx4 v[220:221], off
	v_lshl_add_u64 v[220:221], s[34:35], 0, v[128:129]
	s_add_i32 m0, s36, 0x2000
	s_nop 0
	global_load_lds_dwordx4 v[220:221], off
	v_lshl_add_u64 v[220:221], v[224:225], 0, s[16:17]
	s_mov_b32 m0, s42
	s_nop 0
	global_load_lds_dwordx4 v[220:221], off
	v_lshl_add_u64 v[220:221], v[226:227], 0, s[16:17]
	s_mov_b32 m0, s43
	s_nop 0
	global_load_lds_dwordx4 v[220:221], off
	s_waitcnt vmcnt(8)
	s_waitcnt lgkmcnt(0)
	s_barrier
	s_setprio 1
	s_waitcnt lgkmcnt(0)
	v_mfma_f32_16x16x32_bf16 v[60:63], v[140:143], v[186:189], v[60:63]
	v_mfma_f32_16x16x32_bf16 v[56:59], v[158:161], v[186:189], v[56:59]
	v_mfma_f32_16x16x32_bf16 v[44:47], v[140:143], v[194:197], v[44:47]
	v_mfma_f32_16x16x32_bf16 v[40:43], v[158:161], v[194:197], v[40:43]
	v_mfma_f32_16x16x32_bf16 v[28:31], v[140:143], v[202:205], v[28:31]
	v_mfma_f32_16x16x32_bf16 v[24:27], v[158:161], v[202:205], v[24:27]
	v_mfma_f32_16x16x32_bf16 v[12:15], v[140:143], v[212:215], v[12:15]
	v_mfma_f32_16x16x32_bf16 v[8:11], v[158:161], v[212:215], v[8:11]
	v_mfma_f32_16x16x32_bf16 v[60:63], v[154:157], v[190:193], v[60:63]
	v_mfma_f32_16x16x32_bf16 v[56:59], v[162:165], v[190:193], v[56:59]
	v_mfma_f32_16x16x32_bf16 v[44:47], v[154:157], v[198:201], v[44:47]
	v_mfma_f32_16x16x32_bf16 v[40:43], v[162:165], v[198:201], v[40:43]
	v_mfma_f32_16x16x32_bf16 v[28:31], v[154:157], v[208:211], v[28:31]
	v_mfma_f32_16x16x32_bf16 v[24:27], v[162:165], v[208:211], v[24:27]
	v_mfma_f32_16x16x32_bf16 v[12:15], v[154:157], v[216:219], v[12:15]
	v_mfma_f32_16x16x32_bf16 v[8:11], v[162:165], v[216:219], v[8:11]
	s_setprio 0
	s_setprio 1
	v_mfma_f32_16x16x32_bf16 v[52:55], v[166:169], v[186:189], v[52:55]
	v_mfma_f32_16x16x32_bf16 v[48:51], v[178:181], v[186:189], v[48:51]
	v_mfma_f32_16x16x32_bf16 v[36:39], v[166:169], v[194:197], v[36:39]
	v_mfma_f32_16x16x32_bf16 v[32:35], v[178:181], v[194:197], v[32:35]
	v_mfma_f32_16x16x32_bf16 v[20:23], v[166:169], v[202:205], v[20:23]
	v_mfma_f32_16x16x32_bf16 v[16:19], v[178:181], v[202:205], v[16:19]
	v_mfma_f32_16x16x32_bf16 v[4:7], v[166:169], v[212:215], v[4:7]
	v_mfma_f32_16x16x32_bf16 v[0:3], v[178:181], v[212:215], v[0:3]
	v_mfma_f32_16x16x32_bf16 v[52:55], v[172:175], v[190:193], v[52:55]
	v_mfma_f32_16x16x32_bf16 v[48:51], v[182:185], v[190:193], v[48:51]
	v_mfma_f32_16x16x32_bf16 v[36:39], v[172:175], v[198:201], v[36:39]
	v_mfma_f32_16x16x32_bf16 v[32:35], v[182:185], v[198:201], v[32:35]
	v_mfma_f32_16x16x32_bf16 v[20:23], v[172:175], v[208:211], v[20:23]
	v_mfma_f32_16x16x32_bf16 v[16:19], v[182:185], v[208:211], v[16:19]
	v_mfma_f32_16x16x32_bf16 v[4:7], v[172:175], v[216:219], v[4:7]
	v_mfma_f32_16x16x32_bf16 v[0:3], v[182:185], v[216:219], v[0:3]
	s_setprio 0
	s_add_i32 s49, s49, 2
	s_add_u32 s30, s30, 0x100
	s_addc_u32 s31, s31, 0
	s_add_u32 s47, s47, 0x100
	s_addc_u32 s48, s48, 0
	s_cmp_gt_u32 s49, 13
	s_barrier
	s_cbranch_scc0 .LBB0_1604
	s_and_b64 vcc, exec, s[18:19]
	s_cbranch_vccz .LBB0_1607
	s_barrier

; #define PG8_STAGE(bufoff, gbase, voff) do { _Pragma("unroll") for (int _i = 0; _i < 2; ++_i) \
;         __builtin_amdgcn_global_load_lds((const unsigned*)((const char*)(gbase) + (voff)[_i]), (PG8_LAS unsigned*)(lds + (bufoff) + ldsw + _i * 8192), 16, 0, 0); } while (0)
; #define PG8_LDA(dst, b, h) do { _Pragma("unroll") for (int m = 0; m < 4; ++m) _Pragma("unroll") for (int k = 0; k < 2; ++k) dst[m][k] = *(const PG8_LAS bf16x8*)(lds + PG8_SA(b, h) + aoff + m * 2048 + k * 1024); } while (0)
; #define PG8_LDB(dst, b, h) do { _Pragma("unroll") for (int n = 0; n < 2; ++n) _Pragma("unroll") for (int k = 0; k < 2; ++k) dst[n][k] = *(const PG8_LAS bf16x8*)(lds + PG8_SB(b, h) + boff + n * 2048 + k * 1024); } while (0)
; #define PG8_MMA(ai, bj, At, Bt) do { __builtin_amdgcn_s_setprio(1); _Pragma("unroll") for (int m = 0; m < 4; ++m) _Pragma("unroll") for (int n = 0; n < 2; ++n) _Pragma("unroll") for (int k = 0; k < 2; ++k) \
;         acc[ai][bj][m][n] = __builtin_amdgcn_mfma_f32_16x16x32_bf16(Bt[n][k], At[m][k], acc[ai][bj][m][n], 0, 0, 0); __builtin_amdgcn_s_setprio(0); } while (0)
; #define PG8_WAIT_V(n) asm volatile("s_waitcnt vmcnt(" #n ")" ::: "memory")
; #define PG8_WAIT_L(n) asm volatile("s_waitcnt lgkmcnt(" #n ")" ::: "memory")
; #define PG8_BAR __builtin_amdgcn_s_barrier()
; #define PG8_SCHED __builtin_amdgcn_sched_barrier(0)
; template <class Epi, class Sched, bool ALIGN_EPI = false, bool SP2 = false>
; __device__ __forceinline__ void gemm_phase(PG8_LAS unsigned char* lds, const Gemm g, const Sched& S, const Epi& E) {
;     ...
;             PG8_LDB(B0, 0, 0); PG8_LDB(B1, 0, 1); PG8_SCHED; PG8_LDA(At, 0, 0); PG8_STAGE(PG8_SA(1, 1), a1 + hstep, voffA);
;             PG8_WAIT_V(8); PG8_WAIT_L(0); PG8_BAR; PG8_MMA(0, 0, At, B0); PG8_MMA(0, 1, At, B1); PG8_BAR; PG8_SCHED;
;             PG8_LDA(At, 0, 1); PG8_STAGE(PG8_SB(0, 0), b2, voffB); PG8_STAGE(PG8_SB(0, 1), b2 + hstep, voffB); PG8_STAGE(PG8_SA(0, 0), a2, voffA);
;             PG8_WAIT_V(8); PG8_WAIT_L(0); PG8_BAR; PG8_MMA(1, 0, At, B0); PG8_MMA(1, 1, At, B1); PG8_BAR; PG8_SCHED;
.LBB0_1630:
	ds_read_b128 v[142:145], v156
	ds_read_b128 v[146:149], v156 offset:1024
	ds_read_b128 v[160:163], v156 offset:2048
	ds_read_b128 v[164:167], v156 offset:3072
	ds_read_b128 v[168:171], v157
	ds_read_b128 v[172:175], v157 offset:1024
	ds_read_b128 v[178:181], v157 offset:2048
	ds_read_b128 v[182:185], v157 offset:3072
	s_add_u32 s36, s34, 0xfffe0080
	s_addc_u32 s37, s35, -1
	s_cmp_eq_u32 s56, 4
	s_cselect_b32 s39, s29, s37
	s_cselect_b32 s38, s28, s36
	s_cselect_b32 s37, s31, s27
	s_cselect_b32 s36, s30, s25
	v_lshl_add_u64 v[220:221], s[34:35], 0, v[138:139]
	s_add_i32 m0, s41, 0xc000
	ds_read_b128 v[186:189], v158
	ds_read_b128 v[190:193], v158 offset:1024
	ds_read_b128 v[194:197], v158 offset:2048
	ds_read_b128 v[198:201], v158 offset:3072
	ds_read_b128 v[202:205], v158 offset:4096
	ds_read_b128 v[208:211], v158 offset:5120
	ds_read_b128 v[212:215], v158 offset:6144
	ds_read_b128 v[216:219], v158 offset:7168
	global_load_lds_dwordx4 v[220:221], off
	v_lshl_add_u64 v[220:221], s[34:35], 0, v[140:141]
	s_add_i32 m0, s41, 0xe000
	s_nop 0
	global_load_lds_dwordx4 v[220:221], off
	s_waitcnt vmcnt(8)
	s_waitcnt lgkmcnt(0)
	s_barrier
	s_setprio 1
	s_waitcnt lgkmcnt(0)
	v_mfma_f32_16x16x32_bf16 v[124:127], v[142:145], v[186:189], v[124:127]
	v_mfma_f32_16x16x32_bf16 v[120:123], v[160:163], v[186:189], v[120:123]
	v_mfma_f32_16x16x32_bf16 v[108:111], v[142:145], v[194:197], v[108:111]
	v_mfma_f32_16x16x32_bf16 v[104:107], v[160:163], v[194:197], v[104:107]
	v_mfma_f32_16x16x32_bf16 v[92:95], v[142:145], v[202:205], v[92:95]
	v_mfma_f32_16x16x32_bf16 v[88:91], v[160:163], v[202:205], v[88:91]
	v_mfma_f32_16x16x32_bf16 v[76:79], v[142:145], v[212:215], v[76:79]
	v_mfma_f32_16x16x32_bf16 v[72:75], v[160:163], v[212:215], v[72:75]
	v_mfma_f32_16x16x32_bf16 v[124:127], v[146:149], v[190:193], v[124:127]
	v_mfma_f32_16x16x32_bf16 v[120:123], v[164:167], v[190:193], v[120:123]
	v_mfma_f32_16x16x32_bf16 v[108:111], v[146:149], v[198:201], v[108:111]
	v_mfma_f32_16x16x32_bf16 v[104:107], v[164:167], v[198:201], v[104:107]
	v_mfma_f32_16x16x32_bf16 v[92:95], v[146:149], v[208:211], v[92:95]
	v_mfma_f32_16x16x32_bf16 v[88:91], v[164:167], v[208:211], v[88:91]
	v_mfma_f32_16x16x32_bf16 v[76:79], v[146:149], v[216:219], v[76:79]
	v_mfma_f32_16x16x32_bf16 v[72:75], v[164:167], v[216:219], v[72:75]
	s_setprio 0
	s_setprio 1
	v_mfma_f32_16x16x32_bf16 v[116:119], v[168:171], v[186:189], v[116:119]
	v_mfma_f32_16x16x32_bf16 v[112:115], v[178:181], v[186:189], v[112:115]
	v_mfma_f32_16x16x32_bf16 v[100:103], v[168:171], v[194:197], v[100:103]
	v_mfma_f32_16x16x32_bf16 v[96:99], v[178:181], v[194:197], v[96:99]
	v_mfma_f32_16x16x32_bf16 v[84:87], v[168:171], v[202:205], v[84:87]
	v_mfma_f32_16x16x32_bf16 v[80:83], v[178:181], v[202:205], v[80:83]
	v_mfma_f32_16x16x32_bf16 v[68:71], v[168:171], v[212:215], v[68:71]
	v_mfma_f32_16x16x32_bf16 v[64:67], v[178:181], v[212:215], v[64:67]
	v_mfma_f32_16x16x32_bf16 v[116:119], v[172:175], v[190:193], v[116:119]
	v_mfma_f32_16x16x32_bf16 v[112:115], v[182:185], v[190:193], v[112:115]
	v_mfma_f32_16x16x32_bf16 v[100:103], v[172:175], v[198:201], v[100:103]
	v_mfma_f32_16x16x32_bf16 v[96:99], v[182:185], v[198:201], v[96:99]
	v_mfma_f32_16x16x32_bf16 v[84:87], v[172:175], v[208:211], v[84:87]
	v_mfma_f32_16x16x32_bf16 v[80:83], v[182:185], v[208:211], v[80:83]
	v_mfma_f32_16x16x32_bf16 v[68:71], v[172:175], v[216:219], v[68:71]
	v_mfma_f32_16x16x32_bf16 v[64:67], v[182:185], v[216:219], v[64:67]
	s_setprio 0
	s_barrier
	s_add_i32 s57, s50, s40
	v_lshl_add_u64 v[220:221], s[36:37], 0, v[130:131]
	s_mov_b32 m0, s57
	ds_read_b128 v[186:189], v158 offset:16384
	ds_read_b128 v[190:193], v158 offset:17408
	ds_read_b128 v[194:197], v158 offset:18432
	ds_read_b128 v[198:201], v158 offset:19456
	ds_read_b128 v[202:205], v158 offset:20480
	ds_read_b128 v[208:211], v158 offset:21504
	ds_read_b128 v[212:215], v158 offset:22528
	ds_read_b128 v[216:219], v158 offset:23552
	global_load_lds_dwordx4 v[220:221], off
	s_add_i32 m0, s57, 0x2000
	s_add_u32 s58, s36, 0x20000
	v_lshl_add_u64 v[222:223], s[36:37], 0, v[134:135]
	s_addc_u32 s59, s37, 0
	s_add_i32 s57, s51, s40
	global_load_lds_dwordx4 v[222:223], off
	v_lshl_add_u64 v[224:225], s[58:59], 0, v[130:131]
	s_mov_b32 m0, s57
	v_lshl_add_u64 v[226:227], s[38:39], 0, v[132:133]
	global_load_lds_dwordx4 v[224:225], off
	v_lshl_add_u64 v[224:225], s[58:59], 0, v[134:135]
	s_add_i32 m0, s57, 0x2000
	s_nop 0
	global_load_lds_dwordx4 v[224:225], off
	v_lshl_add_u64 v[224:225], s[38:39], 0, v[128:129]
	s_mov_b32 m0, s41
	s_nop 0
	global_load_lds_dwordx4 v[224:225], off
	s_mov_b32 m0, s42
	s_nop 0
	global_load_lds_dwordx4 v[226:227], off
	s_waitcnt vmcnt(8)
	s_waitcnt lgkmcnt(0)
	s_barrier
; #define PG8_STAGE(bufoff, gbase, voff) do { _Pragma("unroll") for (int _i = 0; _i < 2; ++_i) \
;         __builtin_amdgcn_global_load_lds((const unsigned*)((const char*)(gbase) + (voff)[_i]), (PG8_LAS unsigned*)(lds + (bufoff) + ldsw + _i * 8192), 16, 0, 0); } while (0)
; #define PG8_LDA(dst, b, h) do { _Pragma("unroll") for (int m = 0; m < 4; ++m) _Pragma("unroll") for (int k = 0; k < 2; ++k) dst[m][k] = *(const PG8_LAS bf16x8*)(lds + PG8_SA(b, h) + aoff + m * 2048 + k * 1024); } while (0)
; #define PG8_LDB(dst, b, h) do { _Pragma("unroll") for (int n = 0; n < 2; ++n) _Pragma("unroll") for (int k = 0; k < 2; ++k) dst[n][k] = *(const PG8_LAS bf16x8*)(lds + PG8_SB(b, h) + boff + n * 2048 + k * 1024); } while (0)
; #define PG8_MMA(ai, bj, At, Bt) do { __builtin_amdgcn_s_setprio(1); _Pragma("unroll") for (int m = 0; m < 4; ++m) _Pragma("unroll") for (int n = 0; n < 2; ++n) _Pragma("unroll") for (int k = 0; k < 2; ++k) \
;         acc[ai][bj][m][n] = __builtin_amdgcn_mfma_f32_16x16x32_bf16(Bt[n][k], At[m][k], acc[ai][bj][m][n], 0, 0, 0); __builtin_amdgcn_s_setprio(0); } while (0)
; #define PG8_WAIT_V(n) asm volatile("s_waitcnt vmcnt(" #n ")" ::: "memory")
; #define PG8_WAIT_L(n) asm volatile("s_waitcnt lgkmcnt(" #n ")" ::: "memory")
; #define PG8_BAR __builtin_amdgcn_s_barrier()
; #define PG8_SCHED __builtin_amdgcn_sched_barrier(0)
; template <class Epi, class Sched, bool ALIGN_EPI = false, bool SP2 = false>
; __device__ __forceinline__ void gemm_phase(PG8_LAS unsigned char* lds, const Gemm g, const Sched& S, const Epi& E) {
;     ...
;             PG8_WAIT_V(8); PG8_WAIT_L(0); PG8_BAR; PG8_MMA(1, 0, At, B0); PG8_MMA(1, 1, At, B1); PG8_BAR; PG8_SCHED;
;             PG8_LDB(B0, 1, 0); PG8_LDB(B1, 1, 1); PG8_SCHED; PG8_LDA(At, 1, 0); PG8_STAGE(PG8_SA(0, 1), a2 + hstep, voffA);
;             PG8_WAIT_V(8); PG8_WAIT_L(0); PG8_BAR; PG8_MMA(0, 0, At, B0); PG8_MMA(0, 1, At, B1); PG8_BAR; PG8_SCHED;
;             PG8_LDA(At, 1, 1); PG8_STAGE(PG8_SB(1, 0), b3, voffB); PG8_STAGE(PG8_SB(1, 1), b3 + hstep, voffB); PG8_STAGE(PG8_SA(1, 0), a3, voffA);
	s_setprio 1
	s_waitcnt lgkmcnt(0)
	v_mfma_f32_16x16x32_bf16 v[60:63], v[142:145], v[186:189], v[60:63]
	v_mfma_f32_16x16x32_bf16 v[56:59], v[160:163], v[186:189], v[56:59]
	v_mfma_f32_16x16x32_bf16 v[44:47], v[142:145], v[194:197], v[44:47]
	v_mfma_f32_16x16x32_bf16 v[40:43], v[160:163], v[194:197], v[40:43]
	v_mfma_f32_16x16x32_bf16 v[28:31], v[142:145], v[202:205], v[28:31]
	v_mfma_f32_16x16x32_bf16 v[24:27], v[160:163], v[202:205], v[24:27]
	v_mfma_f32_16x16x32_bf16 v[12:15], v[142:145], v[212:215], v[12:15]
	v_mfma_f32_16x16x32_bf16 v[8:11], v[160:163], v[212:215], v[8:11]
	v_mfma_f32_16x16x32_bf16 v[60:63], v[146:149], v[190:193], v[60:63]
	v_mfma_f32_16x16x32_bf16 v[56:59], v[164:167], v[190:193], v[56:59]
	v_mfma_f32_16x16x32_bf16 v[44:47], v[146:149], v[198:201], v[44:47]
	v_mfma_f32_16x16x32_bf16 v[40:43], v[164:167], v[198:201], v[40:43]
	v_mfma_f32_16x16x32_bf16 v[28:31], v[146:149], v[208:211], v[28:31]
	v_mfma_f32_16x16x32_bf16 v[24:27], v[164:167], v[208:211], v[24:27]
	v_mfma_f32_16x16x32_bf16 v[12:15], v[146:149], v[216:219], v[12:15]
	v_mfma_f32_16x16x32_bf16 v[8:11], v[164:167], v[216:219], v[8:11]
	s_setprio 0
	s_setprio 1
	v_mfma_f32_16x16x32_bf16 v[52:55], v[168:171], v[186:189], v[52:55]
	v_mfma_f32_16x16x32_bf16 v[48:51], v[178:181], v[186:189], v[48:51]
	v_mfma_f32_16x16x32_bf16 v[36:39], v[168:171], v[194:197], v[36:39]
	v_mfma_f32_16x16x32_bf16 v[32:35], v[178:181], v[194:197], v[32:35]
	v_mfma_f32_16x16x32_bf16 v[20:23], v[168:171], v[202:205], v[20:23]
	v_mfma_f32_16x16x32_bf16 v[16:19], v[178:181], v[202:205], v[16:19]
	v_mfma_f32_16x16x32_bf16 v[4:7], v[168:171], v[212:215], v[4:7]
	v_mfma_f32_16x16x32_bf16 v[0:3], v[178:181], v[212:215], v[0:3]
	v_mfma_f32_16x16x32_bf16 v[52:55], v[172:175], v[190:193], v[52:55]
	v_mfma_f32_16x16x32_bf16 v[48:51], v[182:185], v[190:193], v[48:51]
	v_mfma_f32_16x16x32_bf16 v[36:39], v[172:175], v[198:201], v[36:39]
	v_mfma_f32_16x16x32_bf16 v[32:35], v[182:185], v[198:201], v[32:35]
	v_mfma_f32_16x16x32_bf16 v[20:23], v[172:175], v[208:211], v[20:23]
	v_mfma_f32_16x16x32_bf16 v[16:19], v[182:185], v[208:211], v[16:19]
	v_mfma_f32_16x16x32_bf16 v[4:7], v[172:175], v[216:219], v[4:7]
	v_mfma_f32_16x16x32_bf16 v[0:3], v[182:185], v[216:219], v[0:3]
	s_setprio 0
	s_barrier
	v_add_u32_e32 v136, s52, v151
	ds_read_b128 v[142:145], v136
	ds_read_b128 v[146:149], v136 offset:1024
	ds_read_b128 v[160:163], v136 offset:2048
	ds_read_b128 v[164:167], v136 offset:3072
	v_add_u32_e32 v136, s53, v151
	ds_read_b128 v[168:171], v136
	ds_read_b128 v[172:175], v136 offset:1024
	ds_read_b128 v[178:181], v136 offset:2048
	ds_read_b128 v[182:185], v136 offset:3072
	s_add_u32 s38, s38, 0x20000
	s_addc_u32 s39, s39, 0
	s_mov_b32 m0, s43
	v_lshl_add_u64 v[228:229], s[38:39], 0, v[128:129]
	ds_read_b128 v[186:189], v158 offset:32768
	ds_read_b128 v[190:193], v158 offset:33792
	ds_read_b128 v[194:197], v158 offset:34816
	ds_read_b128 v[198:201], v158 offset:35840
	ds_read_b128 v[202:205], v158 offset:36864
	ds_read_b128 v[208:211], v158 offset:37888
	ds_read_b128 v[212:215], v158 offset:38912
	ds_read_b128 v[216:219], v158 offset:39936
	global_load_lds_dwordx4 v[228:229], off
	v_lshl_add_u64 v[228:229], s[38:39], 0, v[132:133]
	s_mov_b32 m0, s44
	s_nop 0
	global_load_lds_dwordx4 v[228:229], off
	s_waitcnt vmcnt(8)
	s_waitcnt lgkmcnt(0)
	s_barrier
	s_setprio 1
	s_waitcnt lgkmcnt(0)
	v_mfma_f32_16x16x32_bf16 v[124:127], v[142:145], v[186:189], v[124:127]
	v_mfma_f32_16x16x32_bf16 v[120:123], v[160:163], v[186:189], v[120:123]
	v_mfma_f32_16x16x32_bf16 v[108:111], v[142:145], v[194:197], v[108:111]
	v_mfma_f32_16x16x32_bf16 v[104:107], v[160:163], v[194:197], v[104:107]
	v_mfma_f32_16x16x32_bf16 v[92:95], v[142:145], v[202:205], v[92:95]
	v_mfma_f32_16x16x32_bf16 v[88:91], v[160:163], v[202:205], v[88:91]
	v_mfma_f32_16x16x32_bf16 v[76:79], v[142:145], v[212:215], v[76:79]
	v_mfma_f32_16x16x32_bf16 v[72:75], v[160:163], v[212:215], v[72:75]
	v_mfma_f32_16x16x32_bf16 v[124:127], v[146:149], v[190:193], v[124:127]
	v_mfma_f32_16x16x32_bf16 v[120:123], v[164:167], v[190:193], v[120:123]
	v_mfma_f32_16x16x32_bf16 v[108:111], v[146:149], v[198:201], v[108:111]
	v_mfma_f32_16x16x32_bf16 v[104:107], v[164:167], v[198:201], v[104:107]
	v_mfma_f32_16x16x32_bf16 v[92:95], v[146:149], v[208:211], v[92:95]
	v_mfma_f32_16x16x32_bf16 v[88:91], v[164:167], v[208:211], v[88:91]
	v_mfma_f32_16x16x32_bf16 v[76:79], v[146:149], v[216:219], v[76:79]
	v_mfma_f32_16x16x32_bf16 v[72:75], v[164:167], v[216:219], v[72:75]
	s_setprio 0
	s_setprio 1
	v_mfma_f32_16x16x32_bf16 v[116:119], v[168:171], v[186:189], v[116:119]
	v_mfma_f32_16x16x32_bf16 v[112:115], v[178:181], v[186:189], v[112:115]
	v_mfma_f32_16x16x32_bf16 v[100:103], v[168:171], v[194:197], v[100:103]
	v_mfma_f32_16x16x32_bf16 v[96:99], v[178:181], v[194:197], v[96:99]
	v_mfma_f32_16x16x32_bf16 v[84:87], v[168:171], v[202:205], v[84:87]
	v_mfma_f32_16x16x32_bf16 v[80:83], v[178:181], v[202:205], v[80:83]
	v_mfma_f32_16x16x32_bf16 v[68:71], v[168:171], v[212:215], v[68:71]
	v_mfma_f32_16x16x32_bf16 v[64:67], v[178:181], v[212:215], v[64:67]
	v_mfma_f32_16x16x32_bf16 v[116:119], v[172:175], v[190:193], v[116:119]
	v_mfma_f32_16x16x32_bf16 v[112:115], v[182:185], v[190:193], v[112:115]
	v_mfma_f32_16x16x32_bf16 v[100:103], v[172:175], v[198:201], v[100:103]
	v_mfma_f32_16x16x32_bf16 v[96:99], v[182:185], v[198:201], v[96:99]
	v_mfma_f32_16x16x32_bf16 v[84:87], v[172:175], v[208:211], v[84:87]
	v_mfma_f32_16x16x32_bf16 v[80:83], v[182:185], v[208:211], v[80:83]
	v_mfma_f32_16x16x32_bf16 v[68:71], v[172:175], v[216:219], v[68:71]
	v_mfma_f32_16x16x32_bf16 v[64:67], v[182:185], v[216:219], v[64:67]
	s_setprio 0
	s_barrier
; #define PG8_STAGE(bufoff, gbase, voff) do { _Pragma("unroll") for (int _i = 0; _i < 2; ++_i) \
;         __builtin_amdgcn_global_load_lds((const unsigned*)((const char*)(gbase) + (voff)[_i]), (PG8_LAS unsigned*)(lds + (bufoff) + ldsw + _i * 8192), 16, 0, 0); } while (0)
; #define PG8_LDA(dst, b, h) do { _Pragma("unroll") for (int m = 0; m < 4; ++m) _Pragma("unroll") for (int k = 0; k < 2; ++k) dst[m][k] = *(const PG8_LAS bf16x8*)(lds + PG8_SA(b, h) + aoff + m * 2048 + k * 1024); } while (0)
; #define PG8_MMA(ai, bj, At, Bt) do { __builtin_amdgcn_s_setprio(1); _Pragma("unroll") for (int m = 0; m < 4; ++m) _Pragma("unroll") for (int n = 0; n < 2; ++n) _Pragma("unroll") for (int k = 0; k < 2; ++k) \
;         acc[ai][bj][m][n] = __builtin_amdgcn_mfma_f32_16x16x32_bf16(Bt[n][k], At[m][k], acc[ai][bj][m][n], 0, 0, 0); __builtin_amdgcn_s_setprio(0); } while (0)
; #define PG8_WAIT_V(n) asm volatile("s_waitcnt vmcnt(" #n ")" ::: "memory")
; #define PG8_WAIT_L(n) asm volatile("s_waitcnt lgkmcnt(" #n ")" ::: "memory")
; #define PG8_BAR __builtin_amdgcn_s_barrier()
; #define PG8_SCHED __builtin_amdgcn_sched_barrier(0)
; template <class Epi, class Sched, bool ALIGN_EPI = false, bool SP2 = false>
; __device__ __forceinline__ void gemm_phase(PG8_LAS unsigned char* lds, const Gemm g, const Sched& S, const Epi& E) {
;     ...
;         for (int t = 0; t < nt; t += 2) {
;     ...
;             PG8_LDA(At, 1, 1); PG8_STAGE(PG8_SB(1, 0), b3, voffB); PG8_STAGE(PG8_SB(1, 1), b3 + hstep, voffB); PG8_STAGE(PG8_SA(1, 0), a3, voffA);
;             PG8_WAIT_V(8); PG8_WAIT_L(0); PG8_BAR; PG8_MMA(1, 0, At, B0); PG8_MMA(1, 1, At, B1); PG8_BAR; PG8_SCHED;
	s_add_i32 s38, s52, s40
	v_lshl_add_u64 v[220:221], v[220:221], 0, s[20:21]
	s_mov_b32 m0, s38
	ds_read_b128 v[186:189], v158 offset:49152
	ds_read_b128 v[190:193], v158 offset:50176
	ds_read_b128 v[194:197], v158 offset:51200
	ds_read_b128 v[198:201], v158 offset:52224
	ds_read_b128 v[202:205], v158 offset:53248
	ds_read_b128 v[208:211], v158 offset:54272
	ds_read_b128 v[212:215], v158 offset:55296
	ds_read_b128 v[216:219], v158 offset:56320
	global_load_lds_dwordx4 v[220:221], off
	s_add_i32 m0, s38, 0x2000
	s_add_u32 s36, s36, 0x20080
	v_lshl_add_u64 v[220:221], v[222:223], 0, s[20:21]
	s_addc_u32 s37, s37, 0
	s_add_i32 s38, s53, s40
	global_load_lds_dwordx4 v[220:221], off
	v_lshl_add_u64 v[220:221], s[36:37], 0, v[130:131]
	s_mov_b32 m0, s38
	s_nop 0
	global_load_lds_dwordx4 v[220:221], off
	v_lshl_add_u64 v[220:221], s[36:37], 0, v[134:135]
	s_add_i32 m0, s38, 0x2000
	s_nop 0
	global_load_lds_dwordx4 v[220:221], off
	v_lshl_add_u64 v[220:221], v[224:225], 0, s[20:21]
	s_mov_b32 m0, s46
	s_nop 0
	global_load_lds_dwordx4 v[220:221], off
	v_lshl_add_u64 v[220:221], v[226:227], 0, s[20:21]
	s_mov_b32 m0, s47
	s_nop 0
	global_load_lds_dwordx4 v[220:221], off
	s_waitcnt vmcnt(8)
	s_waitcnt lgkmcnt(0)
	s_barrier
	s_setprio 1
	s_waitcnt lgkmcnt(0)
	v_mfma_f32_16x16x32_bf16 v[60:63], v[142:145], v[186:189], v[60:63]
	v_mfma_f32_16x16x32_bf16 v[56:59], v[160:163], v[186:189], v[56:59]
	v_mfma_f32_16x16x32_bf16 v[44:47], v[142:145], v[194:197], v[44:47]
	v_mfma_f32_16x16x32_bf16 v[40:43], v[160:163], v[194:197], v[40:43]
	v_mfma_f32_16x16x32_bf16 v[28:31], v[142:145], v[202:205], v[28:31]
	v_mfma_f32_16x16x32_bf16 v[24:27], v[160:163], v[202:205], v[24:27]
	v_mfma_f32_16x16x32_bf16 v[12:15], v[142:145], v[212:215], v[12:15]
	v_mfma_f32_16x16x32_bf16 v[8:11], v[160:163], v[212:215], v[8:11]
	v_mfma_f32_16x16x32_bf16 v[60:63], v[146:149], v[190:193], v[60:63]
	v_mfma_f32_16x16x32_bf16 v[56:59], v[164:167], v[190:193], v[56:59]
	v_mfma_f32_16x16x32_bf16 v[44:47], v[146:149], v[198:201], v[44:47]
	v_mfma_f32_16x16x32_bf16 v[40:43], v[164:167], v[198:201], v[40:43]
	v_mfma_f32_16x16x32_bf16 v[28:31], v[146:149], v[208:211], v[28:31]
	v_mfma_f32_16x16x32_bf16 v[24:27], v[164:167], v[208:211], v[24:27]
	v_mfma_f32_16x16x32_bf16 v[12:15], v[146:149], v[216:219], v[12:15]
	v_mfma_f32_16x16x32_bf16 v[8:11], v[164:167], v[216:219], v[8:11]
	s_setprio 0
	s_setprio 1
	v_mfma_f32_16x16x32_bf16 v[52:55], v[168:171], v[186:189], v[52:55]
	v_mfma_f32_16x16x32_bf16 v[48:51], v[178:181], v[186:189], v[48:51]
	v_mfma_f32_16x16x32_bf16 v[36:39], v[168:171], v[194:197], v[36:39]
	v_mfma_f32_16x16x32_bf16 v[32:35], v[178:181], v[194:197], v[32:35]
	v_mfma_f32_16x16x32_bf16 v[20:23], v[168:171], v[202:205], v[20:23]
	v_mfma_f32_16x16x32_bf16 v[16:19], v[178:181], v[202:205], v[16:19]
	v_mfma_f32_16x16x32_bf16 v[4:7], v[168:171], v[212:215], v[4:7]
	v_mfma_f32_16x16x32_bf16 v[0:3], v[178:181], v[212:215], v[0:3]
	v_mfma_f32_16x16x32_bf16 v[52:55], v[172:175], v[190:193], v[52:55]
	v_mfma_f32_16x16x32_bf16 v[48:51], v[182:185], v[190:193], v[48:51]
	v_mfma_f32_16x16x32_bf16 v[36:39], v[172:175], v[198:201], v[36:39]
	v_mfma_f32_16x16x32_bf16 v[32:35], v[182:185], v[198:201], v[32:35]
	v_mfma_f32_16x16x32_bf16 v[20:23], v[172:175], v[208:211], v[20:23]
	v_mfma_f32_16x16x32_bf16 v[16:19], v[182:185], v[208:211], v[16:19]
	v_mfma_f32_16x16x32_bf16 v[4:7], v[172:175], v[216:219], v[4:7]
	v_mfma_f32_16x16x32_bf16 v[0:3], v[182:185], v[216:219], v[0:3]
	s_setprio 0
	s_add_i32 s56, s56, 2
	s_add_u32 s34, s34, 0x100
	s_addc_u32 s35, s35, 0
	s_add_u32 s25, s25, 0x100
	s_addc_u32 s27, s27, 0
	s_cmp_gt_u32 s56, 5
	s_barrier
	s_cbranch_scc0 .LBB0_1630
	s_and_b64 vcc, exec, s[22:23]
	s_cbranch_vccz .LBB0_1633
	s_barrier

; #define PG8_STAGE(bufoff, gbase, voff) do { _Pragma("unroll") for (int _i = 0; _i < 2; ++_i) \
;         __builtin_amdgcn_global_load_lds((const unsigned*)((const char*)(gbase) + (voff)[_i]), (PG8_LAS unsigned*)(lds + (bufoff) + ldsw + _i * 8192), 16, 0, 0); } while (0)
; #define PG8_LDA(dst, b, h) do { _Pragma("unroll") for (int m = 0; m < 4; ++m) _Pragma("unroll") for (int k = 0; k < 2; ++k) dst[m][k] = *(const PG8_LAS bf16x8*)(lds + PG8_SA(b, h) + aoff + m * 2048 + k * 1024); } while (0)
; #define PG8_LDB(dst, b, h) do { _Pragma("unroll") for (int n = 0; n < 2; ++n) _Pragma("unroll") for (int k = 0; k < 2; ++k) dst[n][k] = *(const PG8_LAS bf16x8*)(lds + PG8_SB(b, h) + boff + n * 2048 + k * 1024); } while (0)
; #define PG8_MMA(ai, bj, At, Bt) do { __builtin_amdgcn_s_setprio(1); _Pragma("unroll") for (int m = 0; m < 4; ++m) _Pragma("unroll") for (int n = 0; n < 2; ++n) _Pragma("unroll") for (int k = 0; k < 2; ++k) \
;         acc[ai][bj][m][n] = __builtin_amdgcn_mfma_f32_16x16x32_bf16(Bt[n][k], At[m][k], acc[ai][bj][m][n], 0, 0, 0); __builtin_amdgcn_s_setprio(0); } while (0)
; #define PG8_WAIT_V(n) asm volatile("s_waitcnt vmcnt(" #n ")" ::: "memory")
; #define PG8_WAIT_L(n) asm volatile("s_waitcnt lgkmcnt(" #n ")" ::: "memory")
; #define PG8_BAR __builtin_amdgcn_s_barrier()
; #define PG8_SCHED __builtin_amdgcn_sched_barrier(0)
; template <class Epi, class Sched, bool ALIGN_EPI = false, bool SP2 = false>
; __device__ __forceinline__ void gemm_phase(PG8_LAS unsigned char* lds, const Gemm g, const Sched& S, const Epi& E) {
;     ...
;             PG8_LDB(B0, 0, 0); PG8_LDB(B1, 0, 1); PG8_SCHED; PG8_LDA(At, 0, 0); PG8_STAGE(PG8_SA(1, 1), a1 + hstep, voffA);
;             PG8_WAIT_V(8); PG8_WAIT_L(0); PG8_BAR; PG8_MMA(0, 0, At, B0); PG8_MMA(0, 1, At, B1); PG8_BAR; PG8_SCHED;
;             PG8_LDA(At, 0, 1); PG8_STAGE(PG8_SB(0, 0), b2, voffB); PG8_STAGE(PG8_SB(0, 1), b2 + hstep, voffB); PG8_STAGE(PG8_SA(0, 0), a2, voffA);
;             PG8_WAIT_V(8); PG8_WAIT_L(0); PG8_BAR; PG8_MMA(1, 0, At, B0); PG8_MMA(1, 1, At, B1); PG8_BAR; PG8_SCHED;
.LBB0_1717:
	ds_read_b128 v[144:147], v151
	ds_read_b128 v[156:159], v151 offset:1024
	ds_read_b128 v[160:163], v151 offset:2048
	ds_read_b128 v[164:167], v151 offset:3072
	ds_read_b128 v[168:171], v152
	ds_read_b128 v[172:175], v152 offset:1024
	s_waitcnt lgkmcnt(0)
	ds_read_b128 v[178:181], v152 offset:2048
	ds_read_b128 v[182:185], v152 offset:3072
	s_add_u32 s26, s24, 0xfffc0080
	s_addc_u32 s27, s25, -1
	s_cmp_eq_u32 s51, 12
	s_cselect_b32 s29, s17, s27
	s_cselect_b32 s28, s47, s26
	s_cselect_b32 s27, s15, s50
	s_cselect_b32 s26, s48, s49
	v_lshl_add_u64 v[220:221], s[24:25], 0, v[136:137]
	s_add_i32 m0, s23, 0xc000
	ds_read_b128 v[186:189], v153
	ds_read_b128 v[190:193], v153 offset:1024
	ds_read_b128 v[194:197], v153 offset:2048
	ds_read_b128 v[198:201], v153 offset:3072
	ds_read_b128 v[202:205], v153 offset:4096
	ds_read_b128 v[208:211], v153 offset:5120
	ds_read_b128 v[212:215], v153 offset:6144
	ds_read_b128 v[216:219], v153 offset:7168
	global_load_lds_dwordx4 v[220:221], off
	v_lshl_add_u64 v[220:221], s[24:25], 0, v[138:139]
	s_add_i32 m0, s23, 0xe000
	s_nop 0
	global_load_lds_dwordx4 v[220:221], off
	s_waitcnt vmcnt(8)
	s_waitcnt lgkmcnt(0)
	s_barrier
	s_setprio 1
	s_waitcnt lgkmcnt(0)
	v_mfma_f32_16x16x32_bf16 v[124:127], v[144:147], v[186:189], v[124:127]
	v_mfma_f32_16x16x32_bf16 v[120:123], v[160:163], v[186:189], v[120:123]
	v_mfma_f32_16x16x32_bf16 v[108:111], v[144:147], v[194:197], v[108:111]
	v_mfma_f32_16x16x32_bf16 v[104:107], v[160:163], v[194:197], v[104:107]
	v_mfma_f32_16x16x32_bf16 v[92:95], v[144:147], v[202:205], v[92:95]
	v_mfma_f32_16x16x32_bf16 v[88:91], v[160:163], v[202:205], v[88:91]
	v_mfma_f32_16x16x32_bf16 v[76:79], v[144:147], v[212:215], v[76:79]
	v_mfma_f32_16x16x32_bf16 v[72:75], v[160:163], v[212:215], v[72:75]
	v_mfma_f32_16x16x32_bf16 v[124:127], v[156:159], v[190:193], v[124:127]
	v_mfma_f32_16x16x32_bf16 v[120:123], v[164:167], v[190:193], v[120:123]
	v_mfma_f32_16x16x32_bf16 v[108:111], v[156:159], v[198:201], v[108:111]
	v_mfma_f32_16x16x32_bf16 v[104:107], v[164:167], v[198:201], v[104:107]
	v_mfma_f32_16x16x32_bf16 v[92:95], v[156:159], v[208:211], v[92:95]
	v_mfma_f32_16x16x32_bf16 v[88:91], v[164:167], v[208:211], v[88:91]
	v_mfma_f32_16x16x32_bf16 v[76:79], v[156:159], v[216:219], v[76:79]
	v_mfma_f32_16x16x32_bf16 v[72:75], v[164:167], v[216:219], v[72:75]
	s_setprio 0
	s_setprio 1
	v_mfma_f32_16x16x32_bf16 v[116:119], v[168:171], v[186:189], v[116:119]
	v_mfma_f32_16x16x32_bf16 v[112:115], v[178:181], v[186:189], v[112:115]
	v_mfma_f32_16x16x32_bf16 v[100:103], v[168:171], v[194:197], v[100:103]
	v_mfma_f32_16x16x32_bf16 v[96:99], v[178:181], v[194:197], v[96:99]
	v_mfma_f32_16x16x32_bf16 v[84:87], v[168:171], v[202:205], v[84:87]
	v_mfma_f32_16x16x32_bf16 v[80:83], v[178:181], v[202:205], v[80:83]
	v_mfma_f32_16x16x32_bf16 v[68:71], v[168:171], v[212:215], v[68:71]
	v_mfma_f32_16x16x32_bf16 v[64:67], v[178:181], v[212:215], v[64:67]
	v_mfma_f32_16x16x32_bf16 v[116:119], v[172:175], v[190:193], v[116:119]
	v_mfma_f32_16x16x32_bf16 v[112:115], v[182:185], v[190:193], v[112:115]
	v_mfma_f32_16x16x32_bf16 v[100:103], v[172:175], v[198:201], v[100:103]
	v_mfma_f32_16x16x32_bf16 v[96:99], v[182:185], v[198:201], v[96:99]
	v_mfma_f32_16x16x32_bf16 v[84:87], v[172:175], v[208:211], v[84:87]
	v_mfma_f32_16x16x32_bf16 v[80:83], v[182:185], v[208:211], v[80:83]
	v_mfma_f32_16x16x32_bf16 v[68:71], v[172:175], v[216:219], v[68:71]
	v_mfma_f32_16x16x32_bf16 v[64:67], v[182:185], v[216:219], v[64:67]
	s_setprio 0
	s_barrier
	s_add_i32 s52, s44, s36
	v_lshl_add_u64 v[220:221], s[26:27], 0, v[130:131]
	s_mov_b32 m0, s52
	ds_read_b128 v[186:189], v153 offset:16384
	ds_read_b128 v[190:193], v153 offset:17408
	ds_read_b128 v[194:197], v153 offset:18432
	ds_read_b128 v[198:201], v153 offset:19456
	ds_read_b128 v[202:205], v153 offset:20480
	ds_read_b128 v[208:211], v153 offset:21504
	ds_read_b128 v[212:215], v153 offset:22528
	ds_read_b128 v[216:219], v153 offset:23552
	global_load_lds_dwordx4 v[220:221], off
	s_add_i32 m0, s52, 0x2000
	s_add_u32 s52, s26, 0x40000
	v_lshl_add_u64 v[222:223], s[26:27], 0, v[134:135]
	s_addc_u32 s53, s27, 0
	s_add_i32 s54, s45, s36
	global_load_lds_dwordx4 v[222:223], off
	v_lshl_add_u64 v[224:225], s[52:53], 0, v[130:131]
	s_mov_b32 m0, s54
	v_lshl_add_u64 v[226:227], s[28:29], 0, v[132:133]
	global_load_lds_dwordx4 v[224:225], off
	v_lshl_add_u64 v[224:225], s[52:53], 0, v[134:135]
	s_add_i32 m0, s54, 0x2000
	s_nop 0
	global_load_lds_dwordx4 v[224:225], off
	v_lshl_add_u64 v[224:225], s[28:29], 0, v[128:129]
	s_mov_b32 m0, s23
	s_nop 0
	global_load_lds_dwordx4 v[224:225], off
	s_mov_b32 m0, s37
	s_nop 0
	global_load_lds_dwordx4 v[226:227], off
	s_waitcnt vmcnt(8)
	s_waitcnt lgkmcnt(0)
	s_barrier
; #define PG8_STAGE(bufoff, gbase, voff) do { _Pragma("unroll") for (int _i = 0; _i < 2; ++_i) \
;         __builtin_amdgcn_global_load_lds((const unsigned*)((const char*)(gbase) + (voff)[_i]), (PG8_LAS unsigned*)(lds + (bufoff) + ldsw + _i * 8192), 16, 0, 0); } while (0)
; #define PG8_LDA(dst, b, h) do { _Pragma("unroll") for (int m = 0; m < 4; ++m) _Pragma("unroll") for (int k = 0; k < 2; ++k) dst[m][k] = *(const PG8_LAS bf16x8*)(lds + PG8_SA(b, h) + aoff + m * 2048 + k * 1024); } while (0)
; #define PG8_LDB(dst, b, h) do { _Pragma("unroll") for (int n = 0; n < 2; ++n) _Pragma("unroll") for (int k = 0; k < 2; ++k) dst[n][k] = *(const PG8_LAS bf16x8*)(lds + PG8_SB(b, h) + boff + n * 2048 + k * 1024); } while (0)
; #define PG8_MMA(ai, bj, At, Bt) do { __builtin_amdgcn_s_setprio(1); _Pragma("unroll") for (int m = 0; m < 4; ++m) _Pragma("unroll") for (int n = 0; n < 2; ++n) _Pragma("unroll") for (int k = 0; k < 2; ++k) \
;         acc[ai][bj][m][n] = __builtin_amdgcn_mfma_f32_16x16x32_bf16(Bt[n][k], At[m][k], acc[ai][bj][m][n], 0, 0, 0); __builtin_amdgcn_s_setprio(0); } while (0)
; #define PG8_WAIT_V(n) asm volatile("s_waitcnt vmcnt(" #n ")" ::: "memory")
; #define PG8_WAIT_L(n) asm volatile("s_waitcnt lgkmcnt(" #n ")" ::: "memory")
; #define PG8_BAR __builtin_amdgcn_s_barrier()
; #define PG8_SCHED __builtin_amdgcn_sched_barrier(0)
; template <class Epi, class Sched, bool ALIGN_EPI = false, bool SP2 = false>
; __device__ __forceinline__ void gemm_phase(PG8_LAS unsigned char* lds, const Gemm g, const Sched& S, const Epi& E) {
;     ...
;             PG8_WAIT_V(8); PG8_WAIT_L(0); PG8_BAR; PG8_MMA(1, 0, At, B0); PG8_MMA(1, 1, At, B1); PG8_BAR; PG8_SCHED;
;             PG8_LDB(B0, 1, 0); PG8_LDB(B1, 1, 1); PG8_SCHED; PG8_LDA(At, 1, 0); PG8_STAGE(PG8_SA(0, 1), a2 + hstep, voffA);
;             PG8_WAIT_V(8); PG8_WAIT_L(0); PG8_BAR; PG8_MMA(0, 0, At, B0); PG8_MMA(0, 1, At, B1); PG8_BAR; PG8_SCHED;
	s_setprio 1
	s_waitcnt lgkmcnt(0)
	v_mfma_f32_16x16x32_bf16 v[60:63], v[144:147], v[186:189], v[60:63]
	v_mfma_f32_16x16x32_bf16 v[56:59], v[160:163], v[186:189], v[56:59]
	v_mfma_f32_16x16x32_bf16 v[44:47], v[144:147], v[194:197], v[44:47]
	v_mfma_f32_16x16x32_bf16 v[40:43], v[160:163], v[194:197], v[40:43]
	v_mfma_f32_16x16x32_bf16 v[28:31], v[144:147], v[202:205], v[28:31]
	v_mfma_f32_16x16x32_bf16 v[24:27], v[160:163], v[202:205], v[24:27]
	v_mfma_f32_16x16x32_bf16 v[12:15], v[144:147], v[212:215], v[12:15]
	v_mfma_f32_16x16x32_bf16 v[8:11], v[160:163], v[212:215], v[8:11]
	v_mfma_f32_16x16x32_bf16 v[60:63], v[156:159], v[190:193], v[60:63]
	v_mfma_f32_16x16x32_bf16 v[56:59], v[164:167], v[190:193], v[56:59]
	v_mfma_f32_16x16x32_bf16 v[44:47], v[156:159], v[198:201], v[44:47]
	v_mfma_f32_16x16x32_bf16 v[40:43], v[164:167], v[198:201], v[40:43]
	v_mfma_f32_16x16x32_bf16 v[28:31], v[156:159], v[208:211], v[28:31]
	v_mfma_f32_16x16x32_bf16 v[24:27], v[164:167], v[208:211], v[24:27]
	v_mfma_f32_16x16x32_bf16 v[12:15], v[156:159], v[216:219], v[12:15]
	v_mfma_f32_16x16x32_bf16 v[8:11], v[164:167], v[216:219], v[8:11]
	s_setprio 0
	s_setprio 1
	v_mfma_f32_16x16x32_bf16 v[52:55], v[168:171], v[186:189], v[52:55]
	v_mfma_f32_16x16x32_bf16 v[48:51], v[178:181], v[186:189], v[48:51]
	v_mfma_f32_16x16x32_bf16 v[36:39], v[168:171], v[194:197], v[36:39]
	v_mfma_f32_16x16x32_bf16 v[32:35], v[178:181], v[194:197], v[32:35]
	v_mfma_f32_16x16x32_bf16 v[20:23], v[168:171], v[202:205], v[20:23]
	v_mfma_f32_16x16x32_bf16 v[16:19], v[178:181], v[202:205], v[16:19]
	v_mfma_f32_16x16x32_bf16 v[4:7], v[168:171], v[212:215], v[4:7]
	v_mfma_f32_16x16x32_bf16 v[0:3], v[178:181], v[212:215], v[0:3]
	v_mfma_f32_16x16x32_bf16 v[52:55], v[172:175], v[190:193], v[52:55]
	v_mfma_f32_16x16x32_bf16 v[48:51], v[182:185], v[190:193], v[48:51]
	v_mfma_f32_16x16x32_bf16 v[36:39], v[172:175], v[198:201], v[36:39]
	v_mfma_f32_16x16x32_bf16 v[32:35], v[182:185], v[198:201], v[32:35]
	v_mfma_f32_16x16x32_bf16 v[20:23], v[172:175], v[208:211], v[20:23]
	v_mfma_f32_16x16x32_bf16 v[16:19], v[182:185], v[208:211], v[16:19]
	v_mfma_f32_16x16x32_bf16 v[4:7], v[172:175], v[216:219], v[4:7]
	v_mfma_f32_16x16x32_bf16 v[0:3], v[182:185], v[216:219], v[0:3]
	s_setprio 0
	s_barrier
	s_add_i32 s52, 0, 0x18000
	v_add_u32_e32 v155, s52, v149
	s_add_i32 s53, 0, 0x1c000
	ds_read_b128 v[144:147], v155
	ds_read_b128 v[156:159], v155 offset:1024
	ds_read_b128 v[160:163], v155 offset:2048
	ds_read_b128 v[164:167], v155 offset:3072
	v_add_u32_e32 v155, s53, v149
	ds_read_b128 v[168:171], v155
	ds_read_b128 v[172:175], v155 offset:1024
	ds_read_b128 v[178:181], v155 offset:2048
	ds_read_b128 v[182:185], v155 offset:3072
	s_add_u32 s28, s28, 0x40000
	s_addc_u32 s29, s29, 0
	s_mov_b32 m0, s38
	v_lshl_add_u64 v[228:229], s[28:29], 0, v[128:129]
	ds_read_b128 v[186:189], v153 offset:32768
	ds_read_b128 v[190:193], v153 offset:33792
	ds_read_b128 v[194:197], v153 offset:34816
	ds_read_b128 v[198:201], v153 offset:35840
	ds_read_b128 v[202:205], v153 offset:36864
	ds_read_b128 v[208:211], v153 offset:37888
	ds_read_b128 v[212:215], v153 offset:38912
	ds_read_b128 v[216:219], v153 offset:39936
	global_load_lds_dwordx4 v[228:229], off
	v_lshl_add_u64 v[228:229], s[28:29], 0, v[132:133]
	s_mov_b32 m0, s39
	s_nop 0
	global_load_lds_dwordx4 v[228:229], off
	s_waitcnt vmcnt(8)
	s_waitcnt lgkmcnt(0)
	s_barrier
	s_setprio 1
	s_waitcnt lgkmcnt(0)
	v_mfma_f32_16x16x32_bf16 v[124:127], v[144:147], v[186:189], v[124:127]
	v_mfma_f32_16x16x32_bf16 v[120:123], v[160:163], v[186:189], v[120:123]
	v_mfma_f32_16x16x32_bf16 v[108:111], v[144:147], v[194:197], v[108:111]
	v_mfma_f32_16x16x32_bf16 v[104:107], v[160:163], v[194:197], v[104:107]
	v_mfma_f32_16x16x32_bf16 v[92:95], v[144:147], v[202:205], v[92:95]
	v_mfma_f32_16x16x32_bf16 v[88:91], v[160:163], v[202:205], v[88:91]
	v_mfma_f32_16x16x32_bf16 v[76:79], v[144:147], v[212:215], v[76:79]
	v_mfma_f32_16x16x32_bf16 v[72:75], v[160:163], v[212:215], v[72:75]
	v_mfma_f32_16x16x32_bf16 v[124:127], v[156:159], v[190:193], v[124:127]
	v_mfma_f32_16x16x32_bf16 v[120:123], v[164:167], v[190:193], v[120:123]
	v_mfma_f32_16x16x32_bf16 v[108:111], v[156:159], v[198:201], v[108:111]
	v_mfma_f32_16x16x32_bf16 v[104:107], v[164:167], v[198:201], v[104:107]
	v_mfma_f32_16x16x32_bf16 v[92:95], v[156:159], v[208:211], v[92:95]
	v_mfma_f32_16x16x32_bf16 v[88:91], v[164:167], v[208:211], v[88:91]
	v_mfma_f32_16x16x32_bf16 v[76:79], v[156:159], v[216:219], v[76:79]
	v_mfma_f32_16x16x32_bf16 v[72:75], v[164:167], v[216:219], v[72:75]
	s_setprio 0
	s_setprio 1
	v_mfma_f32_16x16x32_bf16 v[116:119], v[168:171], v[186:189], v[116:119]
	v_mfma_f32_16x16x32_bf16 v[112:115], v[178:181], v[186:189], v[112:115]
	v_mfma_f32_16x16x32_bf16 v[100:103], v[168:171], v[194:197], v[100:103]
	v_mfma_f32_16x16x32_bf16 v[96:99], v[178:181], v[194:197], v[96:99]
	v_mfma_f32_16x16x32_bf16 v[84:87], v[168:171], v[202:205], v[84:87]
	v_mfma_f32_16x16x32_bf16 v[80:83], v[178:181], v[202:205], v[80:83]
	v_mfma_f32_16x16x32_bf16 v[68:71], v[168:171], v[212:215], v[68:71]
	v_mfma_f32_16x16x32_bf16 v[64:67], v[178:181], v[212:215], v[64:67]
	v_mfma_f32_16x16x32_bf16 v[116:119], v[172:175], v[190:193], v[116:119]
	v_mfma_f32_16x16x32_bf16 v[112:115], v[182:185], v[190:193], v[112:115]
	v_mfma_f32_16x16x32_bf16 v[100:103], v[172:175], v[198:201], v[100:103]
	v_mfma_f32_16x16x32_bf16 v[96:99], v[182:185], v[198:201], v[96:99]
	v_mfma_f32_16x16x32_bf16 v[84:87], v[172:175], v[208:211], v[84:87]
	v_mfma_f32_16x16x32_bf16 v[80:83], v[182:185], v[208:211], v[80:83]
	v_mfma_f32_16x16x32_bf16 v[68:71], v[172:175], v[216:219], v[68:71]
	v_mfma_f32_16x16x32_bf16 v[64:67], v[182:185], v[216:219], v[64:67]
	s_setprio 0
	s_barrier
; #define PG8_STAGE(bufoff, gbase, voff) do { _Pragma("unroll") for (int _i = 0; _i < 2; ++_i) \
;         __builtin_amdgcn_global_load_lds((const unsigned*)((const char*)(gbase) + (voff)[_i]), (PG8_LAS unsigned*)(lds + (bufoff) + ldsw + _i * 8192), 16, 0, 0); } while (0)
; #define PG8_LDA(dst, b, h) do { _Pragma("unroll") for (int m = 0; m < 4; ++m) _Pragma("unroll") for (int k = 0; k < 2; ++k) dst[m][k] = *(const PG8_LAS bf16x8*)(lds + PG8_SA(b, h) + aoff + m * 2048 + k * 1024); } while (0)
; #define PG8_MMA(ai, bj, At, Bt) do { __builtin_amdgcn_s_setprio(1); _Pragma("unroll") for (int m = 0; m < 4; ++m) _Pragma("unroll") for (int n = 0; n < 2; ++n) _Pragma("unroll") for (int k = 0; k < 2; ++k) \
;         acc[ai][bj][m][n] = __builtin_amdgcn_mfma_f32_16x16x32_bf16(Bt[n][k], At[m][k], acc[ai][bj][m][n], 0, 0, 0); __builtin_amdgcn_s_setprio(0); } while (0)
; #define PG8_WAIT_V(n) asm volatile("s_waitcnt vmcnt(" #n ")" ::: "memory")
; #define PG8_WAIT_L(n) asm volatile("s_waitcnt lgkmcnt(" #n ")" ::: "memory")
; #define PG8_BAR __builtin_amdgcn_s_barrier()
; #define PG8_SCHED __builtin_amdgcn_sched_barrier(0)
; template <class Epi, class Sched, bool ALIGN_EPI = false, bool SP2 = false>
; __device__ __forceinline__ void gemm_phase(PG8_LAS unsigned char* lds, const Gemm g, const Sched& S, const Epi& E) {
;     ...
;             PG8_LDA(At, 1, 1); PG8_STAGE(PG8_SB(1, 0), b3, voffB); PG8_STAGE(PG8_SB(1, 1), b3 + hstep, voffB); PG8_STAGE(PG8_SA(1, 0), a3, voffA);
;             PG8_WAIT_V(8); PG8_WAIT_L(0); PG8_BAR; PG8_MMA(1, 0, At, B0); PG8_MMA(1, 1, At, B1); PG8_BAR; PG8_SCHED;
	s_add_i32 s28, s52, s36
	v_lshl_add_u64 v[220:221], v[220:221], 0, s[10:11]
	s_mov_b32 m0, s28
	ds_read_b128 v[186:189], v153 offset:49152
	ds_read_b128 v[190:193], v153 offset:50176
	ds_read_b128 v[194:197], v153 offset:51200
	ds_read_b128 v[198:201], v153 offset:52224
	ds_read_b128 v[202:205], v153 offset:53248
	ds_read_b128 v[208:211], v153 offset:54272
	ds_read_b128 v[212:215], v153 offset:55296
	ds_read_b128 v[216:219], v153 offset:56320
	global_load_lds_dwordx4 v[220:221], off
	s_add_i32 m0, s28, 0x2000
	s_add_u32 s26, s26, 0x40080
	v_lshl_add_u64 v[220:221], v[222:223], 0, s[10:11]
	s_addc_u32 s27, s27, 0
	s_add_i32 s28, s53, s36
	global_load_lds_dwordx4 v[220:221], off
	v_lshl_add_u64 v[220:221], s[26:27], 0, v[130:131]
	s_mov_b32 m0, s28
	s_nop 0
	global_load_lds_dwordx4 v[220:221], off
	v_lshl_add_u64 v[220:221], s[26:27], 0, v[134:135]
	s_add_i32 m0, s28, 0x2000
	s_nop 0
	global_load_lds_dwordx4 v[220:221], off
	v_lshl_add_u64 v[220:221], v[224:225], 0, s[10:11]
	s_mov_b32 m0, s41
	s_nop 0
	global_load_lds_dwordx4 v[220:221], off
	v_lshl_add_u64 v[220:221], v[226:227], 0, s[10:11]
	s_mov_b32 m0, s42
	s_nop 0
	global_load_lds_dwordx4 v[220:221], off
	s_waitcnt vmcnt(8)
	s_waitcnt lgkmcnt(0)
	s_barrier
	s_setprio 1
	s_waitcnt lgkmcnt(0)
	v_mfma_f32_16x16x32_bf16 v[60:63], v[144:147], v[186:189], v[60:63]
	v_mfma_f32_16x16x32_bf16 v[56:59], v[160:163], v[186:189], v[56:59]
	v_mfma_f32_16x16x32_bf16 v[44:47], v[144:147], v[194:197], v[44:47]
	v_mfma_f32_16x16x32_bf16 v[40:43], v[160:163], v[194:197], v[40:43]
	v_mfma_f32_16x16x32_bf16 v[28:31], v[144:147], v[202:205], v[28:31]
	v_mfma_f32_16x16x32_bf16 v[24:27], v[160:163], v[202:205], v[24:27]
	v_mfma_f32_16x16x32_bf16 v[12:15], v[144:147], v[212:215], v[12:15]
	v_mfma_f32_16x16x32_bf16 v[8:11], v[160:163], v[212:215], v[8:11]
	v_mfma_f32_16x16x32_bf16 v[60:63], v[156:159], v[190:193], v[60:63]
	v_mfma_f32_16x16x32_bf16 v[56:59], v[164:167], v[190:193], v[56:59]
	v_mfma_f32_16x16x32_bf16 v[44:47], v[156:159], v[198:201], v[44:47]
	v_mfma_f32_16x16x32_bf16 v[40:43], v[164:167], v[198:201], v[40:43]
	v_mfma_f32_16x16x32_bf16 v[28:31], v[156:159], v[208:211], v[28:31]
	v_mfma_f32_16x16x32_bf16 v[24:27], v[164:167], v[208:211], v[24:27]
	v_mfma_f32_16x16x32_bf16 v[12:15], v[156:159], v[216:219], v[12:15]
	v_mfma_f32_16x16x32_bf16 v[8:11], v[164:167], v[216:219], v[8:11]
	s_setprio 0
	s_setprio 1
	v_mfma_f32_16x16x32_bf16 v[52:55], v[168:171], v[186:189], v[52:55]
	v_mfma_f32_16x16x32_bf16 v[48:51], v[178:181], v[186:189], v[48:51]
	v_mfma_f32_16x16x32_bf16 v[36:39], v[168:171], v[194:197], v[36:39]
	v_mfma_f32_16x16x32_bf16 v[32:35], v[178:181], v[194:197], v[32:35]
	v_mfma_f32_16x16x32_bf16 v[20:23], v[168:171], v[202:205], v[20:23]
	v_mfma_f32_16x16x32_bf16 v[16:19], v[178:181], v[202:205], v[16:19]
	v_mfma_f32_16x16x32_bf16 v[4:7], v[168:171], v[212:215], v[4:7]
	v_mfma_f32_16x16x32_bf16 v[0:3], v[178:181], v[212:215], v[0:3]
	v_mfma_f32_16x16x32_bf16 v[52:55], v[172:175], v[190:193], v[52:55]
	v_mfma_f32_16x16x32_bf16 v[48:51], v[182:185], v[190:193], v[48:51]
	v_mfma_f32_16x16x32_bf16 v[36:39], v[172:175], v[198:201], v[36:39]
	v_mfma_f32_16x16x32_bf16 v[32:35], v[182:185], v[198:201], v[32:35]
	v_mfma_f32_16x16x32_bf16 v[20:23], v[172:175], v[208:211], v[20:23]
	v_mfma_f32_16x16x32_bf16 v[16:19], v[182:185], v[208:211], v[16:19]
	v_mfma_f32_16x16x32_bf16 v[4:7], v[172:175], v[216:219], v[4:7]
	v_mfma_f32_16x16x32_bf16 v[0:3], v[182:185], v[216:219], v[0:3]
	s_setprio 0
	s_add_i32 s51, s51, 2
	s_add_u32 s24, s24, 0x100
	s_addc_u32 s25, s25, 0
	s_add_u32 s49, s49, 0x100
	s_addc_u32 s50, s50, 0
	s_cmp_gt_u32 s51, 13
	s_barrier
	s_cbranch_scc0 .LBB0_1717
	s_and_b64 vcc, exec, s[12:13]
	s_cbranch_vccz .LBB0_1720
	s_barrier

; #define PG8_STAGE(bufoff, gbase, voff) do { _Pragma("unroll") for (int _i = 0; _i < 2; ++_i) \
;         __builtin_amdgcn_global_load_lds((const unsigned*)((const char*)(gbase) + (voff)[_i]), (PG8_LAS unsigned*)(lds + (bufoff) + ldsw + _i * 8192), 16, 0, 0); } while (0)
; #define PG8_LDA(dst, b, h) do { _Pragma("unroll") for (int m = 0; m < 4; ++m) _Pragma("unroll") for (int k = 0; k < 2; ++k) dst[m][k] = *(const PG8_LAS bf16x8*)(lds + PG8_SA(b, h) + aoff + m * 2048 + k * 1024); } while (0)
; #define PG8_LDB(dst, b, h) do { _Pragma("unroll") for (int n = 0; n < 2; ++n) _Pragma("unroll") for (int k = 0; k < 2; ++k) dst[n][k] = *(const PG8_LAS bf16x8*)(lds + PG8_SB(b, h) + boff + n * 2048 + k * 1024); } while (0)
; #define PG8_MMA(ai, bj, At, Bt) do { __builtin_amdgcn_s_setprio(1); _Pragma("unroll") for (int m = 0; m < 4; ++m) _Pragma("unroll") for (int n = 0; n < 2; ++n) _Pragma("unroll") for (int k = 0; k < 2; ++k) \
;         acc[ai][bj][m][n] = __builtin_amdgcn_mfma_f32_16x16x32_bf16(Bt[n][k], At[m][k], acc[ai][bj][m][n], 0, 0, 0); __builtin_amdgcn_s_setprio(0); } while (0)
; #define PG8_WAIT_V(n) asm volatile("s_waitcnt vmcnt(" #n ")" ::: "memory")
; #define PG8_WAIT_L(n) asm volatile("s_waitcnt lgkmcnt(" #n ")" ::: "memory")
; #define PG8_BAR __builtin_amdgcn_s_barrier()
; #define PG8_SCHED __builtin_amdgcn_sched_barrier(0)
; template <class Epi, class Sched, bool ALIGN_EPI = false, bool SP2 = false>
; __device__ __forceinline__ void gemm_phase(PG8_LAS unsigned char* lds, const Gemm g, const Sched& S, const Epi& E) {
;     ...
;             PG8_LDB(B0, 0, 0); PG8_LDB(B1, 0, 1); PG8_SCHED; PG8_LDA(At, 0, 0); PG8_STAGE(PG8_SA(1, 1), a1 + hstep, voffA);
;             PG8_WAIT_V(8); PG8_WAIT_L(0); PG8_BAR; PG8_MMA(0, 0, At, B0); PG8_MMA(0, 1, At, B1); PG8_BAR; PG8_SCHED;
;             PG8_LDA(At, 0, 1); PG8_STAGE(PG8_SB(0, 0), b2, voffB); PG8_STAGE(PG8_SB(0, 1), b2 + hstep, voffB); PG8_STAGE(PG8_SA(0, 0), a2, voffA);
.LBB0_1756:
	ds_read_b128 v[146:149], v160
	ds_read_b128 v[150:153], v160 offset:1024
	ds_read_b128 v[164:167], v160 offset:2048
	ds_read_b128 v[168:171], v160 offset:3072
	ds_read_b128 v[172:175], v161
	s_waitcnt lgkmcnt(0)
	ds_read_b128 v[178:181], v161 offset:1024
	ds_read_b128 v[182:185], v161 offset:2048
	ds_read_b128 v[186:189], v161 offset:3072
	s_add_u32 s26, s24, 0xfff00080
	s_addc_u32 s27, s25, -1
	s_cmp_eq_u32 s50, 60
	s_cselect_b32 s29, s15, s27
	s_cselect_b32 s28, s21, s26
	s_cselect_b32 s27, s13, s49
	s_cselect_b32 s26, s23, s48
	v_lshl_add_u64 v[224:225], s[24:25], 0, v[138:139]
	s_add_i32 m0, s36, 0xc000
	ds_read_b128 v[190:193], v162
	ds_read_b128 v[194:197], v162 offset:1024
	ds_read_b128 v[198:201], v162 offset:2048
	ds_read_b128 v[202:205], v162 offset:3072
	ds_read_b128 v[208:211], v162 offset:4096
	ds_read_b128 v[212:215], v162 offset:5120
	ds_read_b128 v[216:219], v162 offset:6144
	ds_read_b128 v[220:223], v162 offset:7168
	global_load_lds_dwordx4 v[224:225], off
	v_lshl_add_u64 v[224:225], s[24:25], 0, v[140:141]
	s_add_i32 m0, s36, 0xe000
	s_nop 0
	global_load_lds_dwordx4 v[224:225], off
	s_waitcnt vmcnt(8)
	s_waitcnt lgkmcnt(0)
	s_barrier
	s_setprio 1
	s_waitcnt lgkmcnt(0)
	v_mfma_f32_16x16x32_bf16 v[124:127], v[146:149], v[190:193], v[124:127]
	v_mfma_f32_16x16x32_bf16 v[120:123], v[164:167], v[190:193], v[120:123]
	v_mfma_f32_16x16x32_bf16 v[108:111], v[146:149], v[198:201], v[108:111]
	v_mfma_f32_16x16x32_bf16 v[104:107], v[164:167], v[198:201], v[104:107]
	v_mfma_f32_16x16x32_bf16 v[92:95], v[146:149], v[208:211], v[92:95]
	v_mfma_f32_16x16x32_bf16 v[88:91], v[164:167], v[208:211], v[88:91]
	v_mfma_f32_16x16x32_bf16 v[76:79], v[146:149], v[216:219], v[76:79]
	v_mfma_f32_16x16x32_bf16 v[72:75], v[164:167], v[216:219], v[72:75]
	v_mfma_f32_16x16x32_bf16 v[124:127], v[150:153], v[194:197], v[124:127]
	v_mfma_f32_16x16x32_bf16 v[120:123], v[168:171], v[194:197], v[120:123]
	v_mfma_f32_16x16x32_bf16 v[108:111], v[150:153], v[202:205], v[108:111]
	v_mfma_f32_16x16x32_bf16 v[104:107], v[168:171], v[202:205], v[104:107]
	v_mfma_f32_16x16x32_bf16 v[92:95], v[150:153], v[212:215], v[92:95]
	v_mfma_f32_16x16x32_bf16 v[88:91], v[168:171], v[212:215], v[88:91]
	v_mfma_f32_16x16x32_bf16 v[76:79], v[150:153], v[220:223], v[76:79]
	v_mfma_f32_16x16x32_bf16 v[72:75], v[168:171], v[220:223], v[72:75]
	s_setprio 0
	s_setprio 1
	v_mfma_f32_16x16x32_bf16 v[116:119], v[172:175], v[190:193], v[116:119]
	v_mfma_f32_16x16x32_bf16 v[112:115], v[182:185], v[190:193], v[112:115]
	v_mfma_f32_16x16x32_bf16 v[100:103], v[172:175], v[198:201], v[100:103]
	v_mfma_f32_16x16x32_bf16 v[96:99], v[182:185], v[198:201], v[96:99]
	v_mfma_f32_16x16x32_bf16 v[84:87], v[172:175], v[208:211], v[84:87]
	v_mfma_f32_16x16x32_bf16 v[80:83], v[182:185], v[208:211], v[80:83]
	v_mfma_f32_16x16x32_bf16 v[68:71], v[172:175], v[216:219], v[68:71]
	v_mfma_f32_16x16x32_bf16 v[64:67], v[182:185], v[216:219], v[64:67]
	v_mfma_f32_16x16x32_bf16 v[116:119], v[178:181], v[194:197], v[116:119]
	v_mfma_f32_16x16x32_bf16 v[112:115], v[186:189], v[194:197], v[112:115]
	v_mfma_f32_16x16x32_bf16 v[100:103], v[178:181], v[202:205], v[100:103]
	v_mfma_f32_16x16x32_bf16 v[96:99], v[186:189], v[202:205], v[96:99]
	v_mfma_f32_16x16x32_bf16 v[84:87], v[178:181], v[212:215], v[84:87]
	v_mfma_f32_16x16x32_bf16 v[80:83], v[186:189], v[212:215], v[80:83]
	v_mfma_f32_16x16x32_bf16 v[68:71], v[178:181], v[220:223], v[68:71]
	v_mfma_f32_16x16x32_bf16 v[64:67], v[186:189], v[220:223], v[64:67]
	s_setprio 0
	s_barrier
	s_add_i32 s51, s45, s35
	v_lshl_add_u64 v[224:225], s[26:27], 0, v[130:131]
	s_mov_b32 m0, s51
	ds_read_b128 v[190:193], v162 offset:16384
	ds_read_b128 v[194:197], v162 offset:17408
	ds_read_b128 v[198:201], v162 offset:18432
	ds_read_b128 v[202:205], v162 offset:19456
	ds_read_b128 v[208:211], v162 offset:20480
	ds_read_b128 v[212:215], v162 offset:21504
	ds_read_b128 v[216:219], v162 offset:22528
	ds_read_b128 v[220:223], v162 offset:23552
	global_load_lds_dwordx4 v[224:225], off
	s_add_i32 m0, s51, 0x2000
	s_add_u32 s52, s26, 0x100000
	v_lshl_add_u64 v[226:227], s[26:27], 0, v[134:135]
	s_addc_u32 s53, s27, 0
	s_add_i32 s51, s46, s35
	global_load_lds_dwordx4 v[226:227], off
	v_lshl_add_u64 v[228:229], s[52:53], 0, v[130:131]
	s_mov_b32 m0, s51
	v_lshl_add_u64 v[230:231], s[28:29], 0, v[132:133]
	global_load_lds_dwordx4 v[228:229], off
	v_lshl_add_u64 v[228:229], s[52:53], 0, v[134:135]
	s_add_i32 m0, s51, 0x2000
	s_nop 0
	global_load_lds_dwordx4 v[228:229], off
	v_lshl_add_u64 v[228:229], s[28:29], 0, v[128:129]
	s_mov_b32 m0, s36
	s_nop 0
	global_load_lds_dwordx4 v[228:229], off
	s_mov_b32 m0, s37
	s_nop 0
	global_load_lds_dwordx4 v[230:231], off
	s_waitcnt vmcnt(8)
	s_waitcnt lgkmcnt(0)
	s_barrier
; #define PG8_STAGE(bufoff, gbase, voff) do { _Pragma("unroll") for (int _i = 0; _i < 2; ++_i) \
;         __builtin_amdgcn_global_load_lds((const unsigned*)((const char*)(gbase) + (voff)[_i]), (PG8_LAS unsigned*)(lds + (bufoff) + ldsw + _i * 8192), 16, 0, 0); } while (0)
; #define PG8_LDA(dst, b, h) do { _Pragma("unroll") for (int m = 0; m < 4; ++m) _Pragma("unroll") for (int k = 0; k < 2; ++k) dst[m][k] = *(const PG8_LAS bf16x8*)(lds + PG8_SA(b, h) + aoff + m * 2048 + k * 1024); } while (0)
; #define PG8_LDB(dst, b, h) do { _Pragma("unroll") for (int n = 0; n < 2; ++n) _Pragma("unroll") for (int k = 0; k < 2; ++k) dst[n][k] = *(const PG8_LAS bf16x8*)(lds + PG8_SB(b, h) + boff + n * 2048 + k * 1024); } while (0)
; #define PG8_MMA(ai, bj, At, Bt) do { __builtin_amdgcn_s_setprio(1); _Pragma("unroll") for (int m = 0; m < 4; ++m) _Pragma("unroll") for (int n = 0; n < 2; ++n) _Pragma("unroll") for (int k = 0; k < 2; ++k) \
;         acc[ai][bj][m][n] = __builtin_amdgcn_mfma_f32_16x16x32_bf16(Bt[n][k], At[m][k], acc[ai][bj][m][n], 0, 0, 0); __builtin_amdgcn_s_setprio(0); } while (0)
; #define PG8_WAIT_V(n) asm volatile("s_waitcnt vmcnt(" #n ")" ::: "memory")
; #define PG8_WAIT_L(n) asm volatile("s_waitcnt lgkmcnt(" #n ")" ::: "memory")
; #define PG8_BAR __builtin_amdgcn_s_barrier()
; #define PG8_SCHED __builtin_amdgcn_sched_barrier(0)
; template <class Epi, class Sched, bool ALIGN_EPI = false, bool SP2 = false>
; __device__ __forceinline__ void gemm_phase(PG8_LAS unsigned char* lds, const Gemm g, const Sched& S, const Epi& E) {
;     ...
;             PG8_WAIT_V(8); PG8_WAIT_L(0); PG8_BAR; PG8_MMA(1, 0, At, B0); PG8_MMA(1, 1, At, B1); PG8_BAR; PG8_SCHED;
;             PG8_LDB(B0, 1, 0); PG8_LDB(B1, 1, 1); PG8_SCHED; PG8_LDA(At, 1, 0); PG8_STAGE(PG8_SA(0, 1), a2 + hstep, voffA);
;             PG8_WAIT_V(8); PG8_WAIT_L(0); PG8_BAR; PG8_MMA(0, 0, At, B0); PG8_MMA(0, 1, At, B1); PG8_BAR; PG8_SCHED;
	s_setprio 1
	s_waitcnt lgkmcnt(0)
	v_mfma_f32_16x16x32_bf16 v[60:63], v[146:149], v[190:193], v[60:63]
	v_mfma_f32_16x16x32_bf16 v[56:59], v[164:167], v[190:193], v[56:59]
	v_mfma_f32_16x16x32_bf16 v[44:47], v[146:149], v[198:201], v[44:47]
	v_mfma_f32_16x16x32_bf16 v[40:43], v[164:167], v[198:201], v[40:43]
	v_mfma_f32_16x16x32_bf16 v[28:31], v[146:149], v[208:211], v[28:31]
	v_mfma_f32_16x16x32_bf16 v[24:27], v[164:167], v[208:211], v[24:27]
	v_mfma_f32_16x16x32_bf16 v[12:15], v[146:149], v[216:219], v[12:15]
	v_mfma_f32_16x16x32_bf16 v[8:11], v[164:167], v[216:219], v[8:11]
	v_mfma_f32_16x16x32_bf16 v[60:63], v[150:153], v[194:197], v[60:63]
	v_mfma_f32_16x16x32_bf16 v[56:59], v[168:171], v[194:197], v[56:59]
	v_mfma_f32_16x16x32_bf16 v[44:47], v[150:153], v[202:205], v[44:47]
	v_mfma_f32_16x16x32_bf16 v[40:43], v[168:171], v[202:205], v[40:43]
	v_mfma_f32_16x16x32_bf16 v[28:31], v[150:153], v[212:215], v[28:31]
	v_mfma_f32_16x16x32_bf16 v[24:27], v[168:171], v[212:215], v[24:27]
	v_mfma_f32_16x16x32_bf16 v[12:15], v[150:153], v[220:223], v[12:15]
	v_mfma_f32_16x16x32_bf16 v[8:11], v[168:171], v[220:223], v[8:11]
	s_setprio 0
	s_setprio 1
	v_mfma_f32_16x16x32_bf16 v[52:55], v[172:175], v[190:193], v[52:55]
	v_mfma_f32_16x16x32_bf16 v[48:51], v[182:185], v[190:193], v[48:51]
	v_mfma_f32_16x16x32_bf16 v[36:39], v[172:175], v[198:201], v[36:39]
	v_mfma_f32_16x16x32_bf16 v[32:35], v[182:185], v[198:201], v[32:35]
	v_mfma_f32_16x16x32_bf16 v[20:23], v[172:175], v[208:211], v[20:23]
	v_mfma_f32_16x16x32_bf16 v[16:19], v[182:185], v[208:211], v[16:19]
	v_mfma_f32_16x16x32_bf16 v[4:7], v[172:175], v[216:219], v[4:7]
	v_mfma_f32_16x16x32_bf16 v[0:3], v[182:185], v[216:219], v[0:3]
	v_mfma_f32_16x16x32_bf16 v[52:55], v[178:181], v[194:197], v[52:55]
	v_mfma_f32_16x16x32_bf16 v[48:51], v[186:189], v[194:197], v[48:51]
	v_mfma_f32_16x16x32_bf16 v[36:39], v[178:181], v[202:205], v[36:39]
	v_mfma_f32_16x16x32_bf16 v[32:35], v[186:189], v[202:205], v[32:35]
	v_mfma_f32_16x16x32_bf16 v[20:23], v[178:181], v[212:215], v[20:23]
	v_mfma_f32_16x16x32_bf16 v[16:19], v[186:189], v[212:215], v[16:19]
	v_mfma_f32_16x16x32_bf16 v[4:7], v[178:181], v[220:223], v[4:7]
	v_mfma_f32_16x16x32_bf16 v[0:3], v[186:189], v[220:223], v[0:3]
	s_setprio 0
	s_barrier
	s_add_i32 s51, 0, 0x18000
	v_add_u32_e32 v136, s51, v155
	s_add_i32 s52, 0, 0x1c000
	ds_read_b128 v[146:149], v136
	ds_read_b128 v[150:153], v136 offset:1024
	ds_read_b128 v[164:167], v136 offset:2048
	ds_read_b128 v[168:171], v136 offset:3072
	v_add_u32_e32 v136, s52, v155
	ds_read_b128 v[172:175], v136
	ds_read_b128 v[178:181], v136 offset:1024
	ds_read_b128 v[182:185], v136 offset:2048
	ds_read_b128 v[186:189], v136 offset:3072
	s_add_u32 s28, s28, 0x100000
	s_addc_u32 s29, s29, 0
	s_mov_b32 m0, s38
	v_lshl_add_u64 v[232:233], s[28:29], 0, v[128:129]
	ds_read_b128 v[190:193], v162 offset:32768
	ds_read_b128 v[194:197], v162 offset:33792
	ds_read_b128 v[198:201], v162 offset:34816
	ds_read_b128 v[202:205], v162 offset:35840
	ds_read_b128 v[208:211], v162 offset:36864
	ds_read_b128 v[212:215], v162 offset:37888
	ds_read_b128 v[216:219], v162 offset:38912
	ds_read_b128 v[220:223], v162 offset:39936
	global_load_lds_dwordx4 v[232:233], off
	v_lshl_add_u64 v[232:233], s[28:29], 0, v[132:133]
	s_mov_b32 m0, s39
	s_nop 0
	global_load_lds_dwordx4 v[232:233], off
	s_waitcnt vmcnt(8)
	s_waitcnt lgkmcnt(0)
	s_barrier
	s_setprio 1
	s_waitcnt lgkmcnt(0)
	v_mfma_f32_16x16x32_bf16 v[124:127], v[146:149], v[190:193], v[124:127]
	v_mfma_f32_16x16x32_bf16 v[120:123], v[164:167], v[190:193], v[120:123]
	v_mfma_f32_16x16x32_bf16 v[108:111], v[146:149], v[198:201], v[108:111]
	v_mfma_f32_16x16x32_bf16 v[104:107], v[164:167], v[198:201], v[104:107]
	v_mfma_f32_16x16x32_bf16 v[92:95], v[146:149], v[208:211], v[92:95]
	v_mfma_f32_16x16x32_bf16 v[88:91], v[164:167], v[208:211], v[88:91]
	v_mfma_f32_16x16x32_bf16 v[76:79], v[146:149], v[216:219], v[76:79]
	v_mfma_f32_16x16x32_bf16 v[72:75], v[164:167], v[216:219], v[72:75]
	v_mfma_f32_16x16x32_bf16 v[124:127], v[150:153], v[194:197], v[124:127]
	v_mfma_f32_16x16x32_bf16 v[120:123], v[168:171], v[194:197], v[120:123]
	v_mfma_f32_16x16x32_bf16 v[108:111], v[150:153], v[202:205], v[108:111]
	v_mfma_f32_16x16x32_bf16 v[104:107], v[168:171], v[202:205], v[104:107]
	v_mfma_f32_16x16x32_bf16 v[92:95], v[150:153], v[212:215], v[92:95]
	v_mfma_f32_16x16x32_bf16 v[88:91], v[168:171], v[212:215], v[88:91]
	v_mfma_f32_16x16x32_bf16 v[76:79], v[150:153], v[220:223], v[76:79]
	v_mfma_f32_16x16x32_bf16 v[72:75], v[168:171], v[220:223], v[72:75]
	s_setprio 0
	s_setprio 1
	v_mfma_f32_16x16x32_bf16 v[116:119], v[172:175], v[190:193], v[116:119]
	v_mfma_f32_16x16x32_bf16 v[112:115], v[182:185], v[190:193], v[112:115]
	v_mfma_f32_16x16x32_bf16 v[100:103], v[172:175], v[198:201], v[100:103]
	v_mfma_f32_16x16x32_bf16 v[96:99], v[182:185], v[198:201], v[96:99]
	v_mfma_f32_16x16x32_bf16 v[84:87], v[172:175], v[208:211], v[84:87]
	v_mfma_f32_16x16x32_bf16 v[80:83], v[182:185], v[208:211], v[80:83]
	v_mfma_f32_16x16x32_bf16 v[68:71], v[172:175], v[216:219], v[68:71]
	v_mfma_f32_16x16x32_bf16 v[64:67], v[182:185], v[216:219], v[64:67]
	v_mfma_f32_16x16x32_bf16 v[116:119], v[178:181], v[194:197], v[116:119]
	v_mfma_f32_16x16x32_bf16 v[112:115], v[186:189], v[194:197], v[112:115]
	v_mfma_f32_16x16x32_bf16 v[100:103], v[178:181], v[202:205], v[100:103]
	v_mfma_f32_16x16x32_bf16 v[96:99], v[186:189], v[202:205], v[96:99]
	v_mfma_f32_16x16x32_bf16 v[84:87], v[178:181], v[212:215], v[84:87]
	v_mfma_f32_16x16x32_bf16 v[80:83], v[186:189], v[212:215], v[80:83]
	v_mfma_f32_16x16x32_bf16 v[68:71], v[178:181], v[220:223], v[68:71]
	v_mfma_f32_16x16x32_bf16 v[64:67], v[186:189], v[220:223], v[64:67]
	s_setprio 0
	s_barrier
; #define PG8_STAGE(bufoff, gbase, voff) do { _Pragma("unroll") for (int _i = 0; _i < 2; ++_i) \
;         __builtin_amdgcn_global_load_lds((const unsigned*)((const char*)(gbase) + (voff)[_i]), (PG8_LAS unsigned*)(lds + (bufoff) + ldsw + _i * 8192), 16, 0, 0); } while (0)
; #define PG8_LDA(dst, b, h) do { _Pragma("unroll") for (int m = 0; m < 4; ++m) _Pragma("unroll") for (int k = 0; k < 2; ++k) dst[m][k] = *(const PG8_LAS bf16x8*)(lds + PG8_SA(b, h) + aoff + m * 2048 + k * 1024); } while (0)
; #define PG8_MMA(ai, bj, At, Bt) do { __builtin_amdgcn_s_setprio(1); _Pragma("unroll") for (int m = 0; m < 4; ++m) _Pragma("unroll") for (int n = 0; n < 2; ++n) _Pragma("unroll") for (int k = 0; k < 2; ++k) \
;         acc[ai][bj][m][n] = __builtin_amdgcn_mfma_f32_16x16x32_bf16(Bt[n][k], At[m][k], acc[ai][bj][m][n], 0, 0, 0); __builtin_amdgcn_s_setprio(0); } while (0)
; #define PG8_WAIT_V(n) asm volatile("s_waitcnt vmcnt(" #n ")" ::: "memory")
; #define PG8_WAIT_L(n) asm volatile("s_waitcnt lgkmcnt(" #n ")" ::: "memory")
; #define PG8_BAR __builtin_amdgcn_s_barrier()
; #define PG8_SCHED __builtin_amdgcn_sched_barrier(0)
; template <class Epi, class Sched, bool ALIGN_EPI = false, bool SP2 = false>
; __device__ __forceinline__ void gemm_phase(PG8_LAS unsigned char* lds, const Gemm g, const Sched& S, const Epi& E) {
;     ...
;             PG8_LDA(At, 1, 1); PG8_STAGE(PG8_SB(1, 0), b3, voffB); PG8_STAGE(PG8_SB(1, 1), b3 + hstep, voffB); PG8_STAGE(PG8_SA(1, 0), a3, voffA);
;             PG8_WAIT_V(8); PG8_WAIT_L(0); PG8_BAR; PG8_MMA(1, 0, At, B0); PG8_MMA(1, 1, At, B1); PG8_BAR; PG8_SCHED;
;     ...
;         if constexpr (ALIGN_EPI) { if (wr == 0) PG8_BAR; }
	s_add_i32 s28, s51, s35
	v_lshl_add_u64 v[224:225], v[224:225], 0, s[8:9]
	s_mov_b32 m0, s28
	ds_read_b128 v[190:193], v162 offset:49152
	ds_read_b128 v[194:197], v162 offset:50176
	ds_read_b128 v[198:201], v162 offset:51200
	ds_read_b128 v[202:205], v162 offset:52224
	ds_read_b128 v[208:211], v162 offset:53248
	ds_read_b128 v[212:215], v162 offset:54272
	ds_read_b128 v[216:219], v162 offset:55296
	ds_read_b128 v[220:223], v162 offset:56320
	global_load_lds_dwordx4 v[224:225], off
	s_add_i32 m0, s28, 0x2000
	s_add_u32 s26, s26, 0x100080
	v_lshl_add_u64 v[224:225], v[226:227], 0, s[8:9]
	s_addc_u32 s27, s27, 0
	s_add_i32 s28, s52, s35
	global_load_lds_dwordx4 v[224:225], off
	v_lshl_add_u64 v[224:225], s[26:27], 0, v[130:131]
	s_mov_b32 m0, s28
	s_nop 0
	global_load_lds_dwordx4 v[224:225], off
	v_lshl_add_u64 v[224:225], s[26:27], 0, v[134:135]
	s_add_i32 m0, s28, 0x2000
	s_nop 0
	global_load_lds_dwordx4 v[224:225], off
	v_lshl_add_u64 v[224:225], v[228:229], 0, s[8:9]
	s_mov_b32 m0, s41
	s_nop 0
	global_load_lds_dwordx4 v[224:225], off
	v_lshl_add_u64 v[224:225], v[230:231], 0, s[8:9]
	s_mov_b32 m0, s42
	s_nop 0
	global_load_lds_dwordx4 v[224:225], off
	s_waitcnt vmcnt(8)
	s_waitcnt lgkmcnt(0)
	s_barrier
	s_setprio 1
	s_waitcnt lgkmcnt(0)
	v_mfma_f32_16x16x32_bf16 v[60:63], v[146:149], v[190:193], v[60:63]
	v_mfma_f32_16x16x32_bf16 v[56:59], v[164:167], v[190:193], v[56:59]
	v_mfma_f32_16x16x32_bf16 v[44:47], v[146:149], v[198:201], v[44:47]
	v_mfma_f32_16x16x32_bf16 v[40:43], v[164:167], v[198:201], v[40:43]
	v_mfma_f32_16x16x32_bf16 v[28:31], v[146:149], v[208:211], v[28:31]
	v_mfma_f32_16x16x32_bf16 v[24:27], v[164:167], v[208:211], v[24:27]
	v_mfma_f32_16x16x32_bf16 v[12:15], v[146:149], v[216:219], v[12:15]
	v_mfma_f32_16x16x32_bf16 v[8:11], v[164:167], v[216:219], v[8:11]
	v_mfma_f32_16x16x32_bf16 v[60:63], v[150:153], v[194:197], v[60:63]
	v_mfma_f32_16x16x32_bf16 v[56:59], v[168:171], v[194:197], v[56:59]
	v_mfma_f32_16x16x32_bf16 v[44:47], v[150:153], v[202:205], v[44:47]
	v_mfma_f32_16x16x32_bf16 v[40:43], v[168:171], v[202:205], v[40:43]
	v_mfma_f32_16x16x32_bf16 v[28:31], v[150:153], v[212:215], v[28:31]
	v_mfma_f32_16x16x32_bf16 v[24:27], v[168:171], v[212:215], v[24:27]
	v_mfma_f32_16x16x32_bf16 v[12:15], v[150:153], v[220:223], v[12:15]
	v_mfma_f32_16x16x32_bf16 v[8:11], v[168:171], v[220:223], v[8:11]
	s_setprio 0
	s_setprio 1
	v_mfma_f32_16x16x32_bf16 v[52:55], v[172:175], v[190:193], v[52:55]
	v_mfma_f32_16x16x32_bf16 v[48:51], v[182:185], v[190:193], v[48:51]
	v_mfma_f32_16x16x32_bf16 v[36:39], v[172:175], v[198:201], v[36:39]
	v_mfma_f32_16x16x32_bf16 v[32:35], v[182:185], v[198:201], v[32:35]
	v_mfma_f32_16x16x32_bf16 v[20:23], v[172:175], v[208:211], v[20:23]
	v_mfma_f32_16x16x32_bf16 v[16:19], v[182:185], v[208:211], v[16:19]
	v_mfma_f32_16x16x32_bf16 v[4:7], v[172:175], v[216:219], v[4:7]
	v_mfma_f32_16x16x32_bf16 v[0:3], v[182:185], v[216:219], v[0:3]
	v_mfma_f32_16x16x32_bf16 v[52:55], v[178:181], v[194:197], v[52:55]
	v_mfma_f32_16x16x32_bf16 v[48:51], v[186:189], v[194:197], v[48:51]
	v_mfma_f32_16x16x32_bf16 v[36:39], v[178:181], v[202:205], v[36:39]
	v_mfma_f32_16x16x32_bf16 v[32:35], v[186:189], v[202:205], v[32:35]
	v_mfma_f32_16x16x32_bf16 v[20:23], v[178:181], v[212:215], v[20:23]
	v_mfma_f32_16x16x32_bf16 v[16:19], v[186:189], v[212:215], v[16:19]
	v_mfma_f32_16x16x32_bf16 v[4:7], v[178:181], v[220:223], v[4:7]
	v_mfma_f32_16x16x32_bf16 v[0:3], v[186:189], v[220:223], v[0:3]
	s_setprio 0
	s_add_i32 s50, s50, 2
	s_add_u32 s24, s24, 0x100
	s_addc_u32 s25, s25, 0
	s_add_u32 s48, s48, 0x100
	s_addc_u32 s49, s49, 0
	s_cmp_gt_u32 s50, 61
	s_barrier
	s_cbranch_scc0 .LBB0_1756
	s_and_b64 vcc, exec, s[10:11]
	s_cbranch_vccz .LBB0_1759
	s_barrier
